# merged 4-phase GEMM K-loops without s_setprio toggles (load-part wave no longer deprioritised)
# speedup vs baseline: 1.0133x; 1.0021x over previous
; #define PG8_STAGE(bufoff, gbase, voff) do { _Pragma("unroll") for (int _i = 0; _i < 2; ++_i) \
;         __builtin_amdgcn_global_load_lds((const unsigned*)((const char*)(gbase) + (voff)[_i]), (LAS unsigned*)(lds + (bufoff) + ldsw + _i * 8192), 16, 0, 0); } while (0)
; #define PG8_LDA(dst, b, h) do { _Pragma("unroll") for (int m = 0; m < 4; ++m) _Pragma("unroll") for (int k = 0; k < 2; ++k) dst[m][k] = *(const LAS bf16x8*)(lds + PG8_SA(b, h) + aoff + m * 2048 + k * 1024); } while (0)
; #define PG8_LDB(dst, b, h) do { _Pragma("unroll") for (int n = 0; n < 2; ++n) _Pragma("unroll") for (int k = 0; k < 2; ++k) dst[n][k] = *(const LAS bf16x8*)(lds + PG8_SB(b, h) + boff + n * 2048 + k * 1024); } while (0)
; #define PG8_MMA(ai, bj, At, Bt) do { __builtin_amdgcn_s_setprio(1); _Pragma("unroll") for (int m = 0; m < 4; ++m) _Pragma("unroll") for (int n = 0; n < 2; ++n) _Pragma("unroll") for (int k = 0; k < 2; ++k) \
;         acc[ai][bj][m][n] = __builtin_amdgcn_mfma_f32_16x16x32_bf16(Bt[n][k], At[m][k], acc[ai][bj][m][n], 0, 0, 0); __builtin_amdgcn_s_setprio(0); } while (0)
; #define PG8_WAIT_V(n) asm volatile("s_waitcnt vmcnt(" #n ")" ::: "memory")
; #define PG8_WAIT_L(n) asm volatile("s_waitcnt lgkmcnt(" #n ")" ::: "memory")
; template <class Epi>
; __device__ __forceinline__ void gemm_phase(LAS unsigned char* lds, const Gemm g, const StaticOrder& S, const Epi& E) {
;     ...
;         for (int t = 0; t < nt; t += 2) {
;             const bool last = (t == nt - 2);
;             const char* a1 = cA + (size_t)(t + 1) * kstep;
;             const char* a2 = last ? nA : cA + (size_t)(t + 2) * kstep; const char* b2 = last ? nB : cB + (size_t)(t + 2) * kstep;
;             const char* a3 = a2 + kstep; const char* b3 = b2 + kstep;
;             PG8_LDB(B0, 0, 0); PG8_SCHED; PG8_LDA(At, 0, 0); PG8_STAGE(PG8_SA(1, 1), a1 + hstepA, voffA);
;             PG8_WAIT_L(8); PG8_BAR; PG8_WAIT_L(0); PG8_MMA(0, 0, At, B0); PG8_BAR; PG8_SCHED;
;             PG8_LDB(B1, 0, 1); PG8_STAGE(PG8_SB(0, 0), b2, voffB);
;             PG8_BAR; PG8_WAIT_L(0); PG8_MMA(0, 1, At, B1); PG8_BAR;
;             PG8_LDA(At, 0, 1); PG8_STAGE(PG8_SA(0, 0), a2, voffA);
;             PG8_BAR; PG8_WAIT_L(0); PG8_MMA(1, 0, At, B0); PG8_BAR; PG8_SCHED;
;             PG8_STAGE(PG8_SB(0, 1), b2 + hstepB, voffB);
;             PG8_WAIT_V(6); PG8_BAR; PG8_MMA(1, 1, At, B1); PG8_BAR;
.LBB0_119:
	ds_read_b128 v[146:149], v154
	ds_read_b128 v[158:161], v154 offset:1024
	ds_read_b128 v[162:165], v154 offset:2048
	ds_read_b128 v[166:169], v154 offset:3072
	s_add_u32 s55, s62, 0xfffc0080
	s_addc_u32 s61, s63, -1
	s_cmp_eq_u32 s33, 12
	s_cselect_b32 s67, s57, s61
	s_cselect_b32 s66, s56, s55
	s_cselect_b32 s65, s59, s31
	s_cselect_b32 s64, s58, s9
	v_lshl_add_u64 v[202:203], s[62:63], 0, v[138:139]
	s_add_i32 m0, s68, 0xc000
	ds_read_b128 v[170:173], v155
	ds_read_b128 v[174:177], v155 offset:1024
	ds_read_b128 v[178:181], v155 offset:2048
	ds_read_b128 v[182:185], v155 offset:3072
	ds_read_b128 v[186:189], v155 offset:4096
	ds_read_b128 v[190:193], v155 offset:5120
	ds_read_b128 v[194:197], v155 offset:6144
	ds_read_b128 v[198:201], v155 offset:7168
	global_load_lds_dwordx4 v[202:203], off
	v_lshl_add_u64 v[202:203], s[62:63], 0, v[140:141]
	s_add_i32 m0, s68, 0xe000
	s_nop 0
	global_load_lds_dwordx4 v[202:203], off
	ds_read_b128 v[202:205], v156
	ds_read_b128 v[206:209], v156 offset:1024
	ds_read_b128 v[210:213], v156 offset:2048
	ds_read_b128 v[214:217], v156 offset:3072
	s_waitcnt vmcnt(8) lgkmcnt(0)
	s_barrier
	s_nop 0
	v_mfma_f32_16x16x32_bf16 v[124:127], v[146:149], v[170:173], v[124:127]
	v_mfma_f32_16x16x32_bf16 v[120:123], v[162:165], v[170:173], v[120:123]
	v_mfma_f32_16x16x32_bf16 v[108:111], v[146:149], v[178:181], v[108:111]
	v_mfma_f32_16x16x32_bf16 v[104:107], v[162:165], v[178:181], v[104:107]
	v_mfma_f32_16x16x32_bf16 v[92:95], v[146:149], v[186:189], v[92:95]
	v_mfma_f32_16x16x32_bf16 v[88:91], v[162:165], v[186:189], v[88:91]
	v_mfma_f32_16x16x32_bf16 v[76:79], v[146:149], v[194:197], v[76:79]
	v_mfma_f32_16x16x32_bf16 v[72:75], v[162:165], v[194:197], v[72:75]
	v_mfma_f32_16x16x32_bf16 v[124:127], v[158:161], v[174:177], v[124:127]
	v_mfma_f32_16x16x32_bf16 v[120:123], v[166:169], v[174:177], v[120:123]
	v_mfma_f32_16x16x32_bf16 v[108:111], v[158:161], v[182:185], v[108:111]
	v_mfma_f32_16x16x32_bf16 v[104:107], v[166:169], v[182:185], v[104:107]
	v_mfma_f32_16x16x32_bf16 v[92:95], v[158:161], v[190:193], v[92:95]
	v_mfma_f32_16x16x32_bf16 v[88:91], v[166:169], v[190:193], v[88:91]
	v_mfma_f32_16x16x32_bf16 v[76:79], v[158:161], v[198:201], v[76:79]
	v_mfma_f32_16x16x32_bf16 v[72:75], v[166:169], v[198:201], v[72:75]
	v_mfma_f32_16x16x32_bf16 v[116:119], v[202:205], v[170:173], v[116:119]
	v_mfma_f32_16x16x32_bf16 v[112:115], v[210:213], v[170:173], v[112:115]
	v_mfma_f32_16x16x32_bf16 v[100:103], v[202:205], v[178:181], v[100:103]
	v_mfma_f32_16x16x32_bf16 v[96:99], v[210:213], v[178:181], v[96:99]
	v_mfma_f32_16x16x32_bf16 v[84:87], v[202:205], v[186:189], v[84:87]
	v_mfma_f32_16x16x32_bf16 v[80:83], v[210:213], v[186:189], v[80:83]
	v_mfma_f32_16x16x32_bf16 v[68:71], v[202:205], v[194:197], v[68:71]
	v_mfma_f32_16x16x32_bf16 v[64:67], v[210:213], v[194:197], v[64:67]
	v_mfma_f32_16x16x32_bf16 v[116:119], v[206:209], v[174:177], v[116:119]
	v_mfma_f32_16x16x32_bf16 v[112:115], v[214:217], v[174:177], v[112:115]
	v_mfma_f32_16x16x32_bf16 v[100:103], v[206:209], v[182:185], v[100:103]
	v_mfma_f32_16x16x32_bf16 v[96:99], v[214:217], v[182:185], v[96:99]
	v_mfma_f32_16x16x32_bf16 v[84:87], v[206:209], v[190:193], v[84:87]
	v_mfma_f32_16x16x32_bf16 v[80:83], v[214:217], v[190:193], v[80:83]
	v_mfma_f32_16x16x32_bf16 v[68:71], v[206:209], v[198:201], v[68:71]
	v_mfma_f32_16x16x32_bf16 v[64:67], v[214:217], v[198:201], v[64:67]
	s_nop 0
	s_barrier
	s_add_i32 s55, s78, s35
	v_lshl_add_u64 v[218:219], s[64:65], 0, v[132:133]
	s_mov_b32 m0, s55
	global_load_lds_dwordx4 v[218:219], off
	v_lshl_add_u64 v[220:221], s[64:65], 0, v[136:137]
	s_add_i32 m0, s55, 0x2000
	s_nop 0
	global_load_lds_dwordx4 v[220:221], off
	s_mov_b32 m0, s68
	v_lshl_add_u64 v[222:223], s[66:67], 0, v[130:131]
	ds_read_b128 v[170:173], v155 offset:16384
	ds_read_b128 v[174:177], v155 offset:17408
	ds_read_b128 v[178:181], v155 offset:18432
	ds_read_b128 v[182:185], v155 offset:19456
	ds_read_b128 v[186:189], v155 offset:20480
	ds_read_b128 v[190:193], v155 offset:21504
	ds_read_b128 v[194:197], v155 offset:22528
	ds_read_b128 v[198:201], v155 offset:23552
	global_load_lds_dwordx4 v[222:223], off
	v_lshl_add_u64 v[224:225], s[66:67], 0, v[134:135]
	s_mov_b32 m0, s69
	s_nop 0
	global_load_lds_dwordx4 v[224:225], off
	s_add_u32 s82, s64, 0x40000
	s_addc_u32 s83, s65, 0
	s_add_i32 s55, s79, s35
	v_lshl_add_u64 v[240:241], s[82:83], 0, v[132:133]
	s_mov_b32 m0, s55
	s_nop 0
	global_load_lds_dwordx4 v[240:241], off
	v_lshl_add_u64 v[240:241], s[82:83], 0, v[136:137]
	s_add_i32 m0, s55, 0x2000
	s_nop 0
	global_load_lds_dwordx4 v[240:241], off
	s_waitcnt vmcnt(8) lgkmcnt(0)
	s_barrier
; #define PG8_STAGE(bufoff, gbase, voff) do { _Pragma("unroll") for (int _i = 0; _i < 2; ++_i) \
;         __builtin_amdgcn_global_load_lds((const unsigned*)((const char*)(gbase) + (voff)[_i]), (LAS unsigned*)(lds + (bufoff) + ldsw + _i * 8192), 16, 0, 0); } while (0)
; #define PG8_LDA(dst, b, h) do { _Pragma("unroll") for (int m = 0; m < 4; ++m) _Pragma("unroll") for (int k = 0; k < 2; ++k) dst[m][k] = *(const LAS bf16x8*)(lds + PG8_SA(b, h) + aoff + m * 2048 + k * 1024); } while (0)
; #define PG8_LDB(dst, b, h) do { _Pragma("unroll") for (int n = 0; n < 2; ++n) _Pragma("unroll") for (int k = 0; k < 2; ++k) dst[n][k] = *(const LAS bf16x8*)(lds + PG8_SB(b, h) + boff + n * 2048 + k * 1024); } while (0)
; #define PG8_MMA(ai, bj, At, Bt) do { __builtin_amdgcn_s_setprio(1); _Pragma("unroll") for (int m = 0; m < 4; ++m) _Pragma("unroll") for (int n = 0; n < 2; ++n) _Pragma("unroll") for (int k = 0; k < 2; ++k) \
;         acc[ai][bj][m][n] = __builtin_amdgcn_mfma_f32_16x16x32_bf16(Bt[n][k], At[m][k], acc[ai][bj][m][n], 0, 0, 0); __builtin_amdgcn_s_setprio(0); } while (0)
; #define PG8_WAIT_V(n) asm volatile("s_waitcnt vmcnt(" #n ")" ::: "memory")
; #define PG8_WAIT_L(n) asm volatile("s_waitcnt lgkmcnt(" #n ")" ::: "memory")
; #define PG8_BAR __builtin_amdgcn_s_barrier()
; #define PG8_SCHED __builtin_amdgcn_sched_barrier(0)
; template <class Epi>
; __device__ __forceinline__ void gemm_phase(LAS unsigned char* lds, const Gemm g, const StaticOrder& S, const Epi& E) {
;     ...
;             PG8_LDA(At, 0, 1); PG8_STAGE(PG8_SA(0, 0), a2, voffA);
;             PG8_BAR; PG8_WAIT_L(0); PG8_MMA(1, 0, At, B0); PG8_BAR; PG8_SCHED;
;             PG8_STAGE(PG8_SB(0, 1), b2 + hstepB, voffB);
;             PG8_WAIT_V(6); PG8_BAR; PG8_MMA(1, 1, At, B1); PG8_BAR;
;             PG8_LDB(B0, 1, 0); PG8_SCHED; PG8_LDA(At, 1, 0); PG8_STAGE(PG8_SA(0, 1), a2 + hstepA, voffA);
;             PG8_WAIT_L(8); PG8_BAR; PG8_WAIT_L(0); PG8_MMA(0, 0, At, B0); PG8_BAR; PG8_SCHED;
;             PG8_LDB(B1, 1, 1); PG8_STAGE(PG8_SB(1, 0), b3, voffB);
;             PG8_BAR; PG8_WAIT_L(0); PG8_MMA(0, 1, At, B1); PG8_BAR;
	s_nop 0
	v_mfma_f32_16x16x32_bf16 v[60:63], v[146:149], v[170:173], v[60:63]
	v_mfma_f32_16x16x32_bf16 v[56:59], v[162:165], v[170:173], v[56:59]
	v_mfma_f32_16x16x32_bf16 v[44:47], v[146:149], v[178:181], v[44:47]
	v_mfma_f32_16x16x32_bf16 v[40:43], v[162:165], v[178:181], v[40:43]
	v_mfma_f32_16x16x32_bf16 v[28:31], v[146:149], v[186:189], v[28:31]
	v_mfma_f32_16x16x32_bf16 v[24:27], v[162:165], v[186:189], v[24:27]
	v_mfma_f32_16x16x32_bf16 v[12:15], v[146:149], v[194:197], v[12:15]
	v_mfma_f32_16x16x32_bf16 v[8:11], v[162:165], v[194:197], v[8:11]
	v_mfma_f32_16x16x32_bf16 v[60:63], v[158:161], v[174:177], v[60:63]
	v_mfma_f32_16x16x32_bf16 v[56:59], v[166:169], v[174:177], v[56:59]
	v_mfma_f32_16x16x32_bf16 v[44:47], v[158:161], v[182:185], v[44:47]
	v_mfma_f32_16x16x32_bf16 v[40:43], v[166:169], v[182:185], v[40:43]
	v_mfma_f32_16x16x32_bf16 v[28:31], v[158:161], v[190:193], v[28:31]
	v_mfma_f32_16x16x32_bf16 v[24:27], v[166:169], v[190:193], v[24:27]
	v_mfma_f32_16x16x32_bf16 v[12:15], v[158:161], v[198:201], v[12:15]
	v_mfma_f32_16x16x32_bf16 v[8:11], v[166:169], v[198:201], v[8:11]
	v_mfma_f32_16x16x32_bf16 v[52:55], v[202:205], v[170:173], v[52:55]
	v_mfma_f32_16x16x32_bf16 v[48:51], v[210:213], v[170:173], v[48:51]
	v_mfma_f32_16x16x32_bf16 v[36:39], v[202:205], v[178:181], v[36:39]
	v_mfma_f32_16x16x32_bf16 v[32:35], v[210:213], v[178:181], v[32:35]
	v_mfma_f32_16x16x32_bf16 v[20:23], v[202:205], v[186:189], v[20:23]
	v_mfma_f32_16x16x32_bf16 v[16:19], v[210:213], v[186:189], v[16:19]
	v_mfma_f32_16x16x32_bf16 v[4:7], v[202:205], v[194:197], v[4:7]
	v_mfma_f32_16x16x32_bf16 v[0:3], v[210:213], v[194:197], v[0:3]
	v_mfma_f32_16x16x32_bf16 v[52:55], v[206:209], v[174:177], v[52:55]
	v_mfma_f32_16x16x32_bf16 v[48:51], v[214:217], v[174:177], v[48:51]
	v_mfma_f32_16x16x32_bf16 v[36:39], v[206:209], v[182:185], v[36:39]
	v_mfma_f32_16x16x32_bf16 v[32:35], v[214:217], v[182:185], v[32:35]
	v_mfma_f32_16x16x32_bf16 v[20:23], v[206:209], v[190:193], v[20:23]
	v_mfma_f32_16x16x32_bf16 v[16:19], v[214:217], v[190:193], v[16:19]
	v_mfma_f32_16x16x32_bf16 v[4:7], v[206:209], v[198:201], v[4:7]
	v_mfma_f32_16x16x32_bf16 v[0:3], v[214:217], v[198:201], v[0:3]
	s_nop 0
	s_barrier
	s_add_i32 s55, 0, 0x18000
	v_add_u32_e32 v157, s55, v152
	ds_read_b128 v[146:149], v157
	ds_read_b128 v[158:161], v157 offset:1024
	ds_read_b128 v[162:165], v157 offset:2048
	ds_read_b128 v[166:169], v157 offset:3072
	s_add_u32 s66, s66, 0x40000
	s_addc_u32 s67, s67, 0
	s_mov_b32 m0, s70
	v_lshl_add_u64 v[202:203], s[66:67], 0, v[130:131]
	ds_read_b128 v[170:173], v155 offset:32768
	ds_read_b128 v[174:177], v155 offset:33792
	ds_read_b128 v[178:181], v155 offset:34816
	ds_read_b128 v[182:185], v155 offset:35840
	ds_read_b128 v[186:189], v155 offset:36864
	ds_read_b128 v[190:193], v155 offset:37888
	ds_read_b128 v[194:197], v155 offset:38912
	ds_read_b128 v[198:201], v155 offset:39936
	global_load_lds_dwordx4 v[202:203], off
	v_lshl_add_u64 v[202:203], s[66:67], 0, v[134:135]
	s_mov_b32 m0, s71
	s_nop 0
	global_load_lds_dwordx4 v[202:203], off
	s_add_i32 s61, 0, 0x1c000
	v_add_u32_e32 v157, s61, v152
	ds_read_b128 v[202:205], v157
	ds_read_b128 v[206:209], v157 offset:1024
	ds_read_b128 v[210:213], v157 offset:2048
	ds_read_b128 v[214:217], v157 offset:3072
	s_waitcnt vmcnt(8) lgkmcnt(0)
	s_barrier
	s_nop 0
	v_mfma_f32_16x16x32_bf16 v[124:127], v[146:149], v[170:173], v[124:127]
	v_mfma_f32_16x16x32_bf16 v[120:123], v[162:165], v[170:173], v[120:123]
	v_mfma_f32_16x16x32_bf16 v[108:111], v[146:149], v[178:181], v[108:111]
	v_mfma_f32_16x16x32_bf16 v[104:107], v[162:165], v[178:181], v[104:107]
	v_mfma_f32_16x16x32_bf16 v[92:95], v[146:149], v[186:189], v[92:95]
	v_mfma_f32_16x16x32_bf16 v[88:91], v[162:165], v[186:189], v[88:91]
	v_mfma_f32_16x16x32_bf16 v[76:79], v[146:149], v[194:197], v[76:79]
	v_mfma_f32_16x16x32_bf16 v[72:75], v[162:165], v[194:197], v[72:75]
	v_mfma_f32_16x16x32_bf16 v[124:127], v[158:161], v[174:177], v[124:127]
	v_mfma_f32_16x16x32_bf16 v[120:123], v[166:169], v[174:177], v[120:123]
	v_mfma_f32_16x16x32_bf16 v[108:111], v[158:161], v[182:185], v[108:111]
	v_mfma_f32_16x16x32_bf16 v[104:107], v[166:169], v[182:185], v[104:107]
	v_mfma_f32_16x16x32_bf16 v[92:95], v[158:161], v[190:193], v[92:95]
	v_mfma_f32_16x16x32_bf16 v[88:91], v[166:169], v[190:193], v[88:91]
	v_mfma_f32_16x16x32_bf16 v[76:79], v[158:161], v[198:201], v[76:79]
	v_mfma_f32_16x16x32_bf16 v[72:75], v[166:169], v[198:201], v[72:75]
	v_mfma_f32_16x16x32_bf16 v[116:119], v[202:205], v[170:173], v[116:119]
	v_mfma_f32_16x16x32_bf16 v[112:115], v[210:213], v[170:173], v[112:115]
	v_mfma_f32_16x16x32_bf16 v[100:103], v[202:205], v[178:181], v[100:103]
	v_mfma_f32_16x16x32_bf16 v[96:99], v[210:213], v[178:181], v[96:99]
	v_mfma_f32_16x16x32_bf16 v[84:87], v[202:205], v[186:189], v[84:87]
	v_mfma_f32_16x16x32_bf16 v[80:83], v[210:213], v[186:189], v[80:83]
	v_mfma_f32_16x16x32_bf16 v[68:71], v[202:205], v[194:197], v[68:71]
	v_mfma_f32_16x16x32_bf16 v[64:67], v[210:213], v[194:197], v[64:67]
	v_mfma_f32_16x16x32_bf16 v[116:119], v[206:209], v[174:177], v[116:119]
	v_mfma_f32_16x16x32_bf16 v[112:115], v[214:217], v[174:177], v[112:115]
	v_mfma_f32_16x16x32_bf16 v[100:103], v[206:209], v[182:185], v[100:103]
	v_mfma_f32_16x16x32_bf16 v[96:99], v[214:217], v[182:185], v[96:99]
	v_mfma_f32_16x16x32_bf16 v[84:87], v[206:209], v[190:193], v[84:87]
	v_mfma_f32_16x16x32_bf16 v[80:83], v[214:217], v[190:193], v[80:83]
	v_mfma_f32_16x16x32_bf16 v[68:71], v[206:209], v[198:201], v[68:71]
	v_mfma_f32_16x16x32_bf16 v[64:67], v[214:217], v[198:201], v[64:67]
	s_nop 0
	s_barrier
; __device__ __forceinline__ unsigned pk2(float lo, float hi) { unsigned r; asm("v_cvt_pk_bf16_f32 %0, %1, %2" : "=v"(r) : "v"(lo), "v"(hi)); return r; }
; __device__ __forceinline__ float gelu_t(float x) { return x * __builtin_amdgcn_rcpf(1.f + __expf(-1.5957691216057308f * (x + 0.044715f * x * x * x))); }
; #define PG8_STAGE(bufoff, gbase, voff) do { _Pragma("unroll") for (int _i = 0; _i < 2; ++_i) \
;         __builtin_amdgcn_global_load_lds((const unsigned*)((const char*)(gbase) + (voff)[_i]), (LAS unsigned*)(lds + (bufoff) + ldsw + _i * 8192), 16, 0, 0); } while (0)
; #define PG8_LDA(dst, b, h) do { _Pragma("unroll") for (int m = 0; m < 4; ++m) _Pragma("unroll") for (int k = 0; k < 2; ++k) dst[m][k] = *(const LAS bf16x8*)(lds + PG8_SA(b, h) + aoff + m * 2048 + k * 1024); } while (0)
; #define PG8_LDB(dst, b, h) do { _Pragma("unroll") for (int n = 0; n < 2; ++n) _Pragma("unroll") for (int k = 0; k < 2; ++k) dst[n][k] = *(const LAS bf16x8*)(lds + PG8_SB(b, h) + boff + n * 2048 + k * 1024); } while (0)
;     __device__ __forceinline__ void operator()(const f32x4 (&acc)[2][2][4][2], const Unit& u, int wr, int wc, int fr, int fq) const {
;     ...
;         for (int ai = 0; ai < 2; ++ai)
; #pragma unroll
;             for (int m = 0; m < 4; ++m) { const int row = row0 + ai * HALF + m * 16; u16* rowp = O + (size_t)row * ldc + col0;
; #pragma unroll
;                 for (int bj = 0; bj < 2; ++bj) { f32x4 v0 = acc[ai][bj][m][0], v1 = acc[ai][bj][m][1];
;                     if (col0 + bj * HALF >= gelu_from) { v0 = (f32x4){gelu_t(v0.x), gelu_t(v0.y), gelu_t(v0.z), gelu_t(v0.w)}; v1 = (f32x4){gelu_t(v1.x), gelu_t(v1.y), gelu_t(v1.z), gelu_t(v1.w)}; }
;                     u32x4 w; w.x = pk2(v0[0], v0[1]); w.y = pk2(v0[2], v0[3]); w.z = pk2(v1[0], v1[1]); w.w = pk2(v1[2], v1[3]);
; template <class Epi>
; __device__ __forceinline__ void gemm_phase(LAS unsigned char* lds, const Gemm g, const StaticOrder& S, const Epi& E) {
;     ...
;             PG8_LDB(B1, 1, 1); PG8_STAGE(PG8_SB(1, 0), b3, voffB);
;             PG8_BAR; PG8_WAIT_L(0); PG8_MMA(0, 1, At, B1); PG8_BAR;
;             PG8_LDA(At, 1, 1); PG8_STAGE(PG8_SA(1, 0), a3, voffA);
;             PG8_BAR; PG8_WAIT_L(0); PG8_MMA(1, 0, At, B0); PG8_BAR; PG8_SCHED;
;             PG8_STAGE(PG8_SB(1, 1), b3 + hstepB, voffB);
;             PG8_WAIT_V(6); PG8_BAR; PG8_MMA(1, 1, At, B1); PG8_BAR;
;         }
	s_add_i32 s55, s55, s35
	v_lshl_add_u64 v[218:219], v[218:219], 0, s[28:29]
	s_mov_b32 m0, s55
	global_load_lds_dwordx4 v[218:219], off
	v_lshl_add_u64 v[218:219], v[220:221], 0, s[28:29]
	s_add_i32 m0, s55, 0x2000
	s_nop 0
	global_load_lds_dwordx4 v[218:219], off
	s_mov_b32 m0, s73
	v_lshl_add_u64 v[218:219], v[222:223], 0, s[28:29]
	ds_read_b128 v[170:173], v155 offset:49152
	ds_read_b128 v[174:177], v155 offset:50176
	ds_read_b128 v[178:181], v155 offset:51200
	ds_read_b128 v[182:185], v155 offset:52224
	ds_read_b128 v[186:189], v155 offset:53248
	ds_read_b128 v[190:193], v155 offset:54272
	ds_read_b128 v[194:197], v155 offset:55296
	ds_read_b128 v[198:201], v155 offset:56320
	global_load_lds_dwordx4 v[218:219], off
	v_lshl_add_u64 v[218:219], v[224:225], 0, s[28:29]
	s_mov_b32 m0, s74
	s_nop 0
	global_load_lds_dwordx4 v[218:219], off
	s_add_u32 s64, s64, 0x40080
	s_addc_u32 s65, s65, 0
	s_add_i32 s55, s61, s35
	v_lshl_add_u64 v[240:241], s[64:65], 0, v[132:133]
	s_mov_b32 m0, s55
	s_nop 0
	global_load_lds_dwordx4 v[240:241], off
	v_lshl_add_u64 v[240:241], s[64:65], 0, v[136:137]
	s_add_i32 m0, s55, 0x2000
	s_nop 0
	global_load_lds_dwordx4 v[240:241], off
	s_waitcnt vmcnt(8) lgkmcnt(0)
	s_barrier
	s_nop 0
	v_mfma_f32_16x16x32_bf16 v[60:63], v[146:149], v[170:173], v[60:63]
	v_mfma_f32_16x16x32_bf16 v[56:59], v[162:165], v[170:173], v[56:59]
	v_mfma_f32_16x16x32_bf16 v[44:47], v[146:149], v[178:181], v[44:47]
	v_mfma_f32_16x16x32_bf16 v[40:43], v[162:165], v[178:181], v[40:43]
	v_mfma_f32_16x16x32_bf16 v[28:31], v[146:149], v[186:189], v[28:31]
	v_mfma_f32_16x16x32_bf16 v[24:27], v[162:165], v[186:189], v[24:27]
	v_mfma_f32_16x16x32_bf16 v[12:15], v[146:149], v[194:197], v[12:15]
	v_mfma_f32_16x16x32_bf16 v[8:11], v[162:165], v[194:197], v[8:11]
	v_mfma_f32_16x16x32_bf16 v[60:63], v[158:161], v[174:177], v[60:63]
	v_mfma_f32_16x16x32_bf16 v[56:59], v[166:169], v[174:177], v[56:59]
	v_mfma_f32_16x16x32_bf16 v[44:47], v[158:161], v[182:185], v[44:47]
	v_mfma_f32_16x16x32_bf16 v[40:43], v[166:169], v[182:185], v[40:43]
	v_mfma_f32_16x16x32_bf16 v[28:31], v[158:161], v[190:193], v[28:31]
	v_mfma_f32_16x16x32_bf16 v[24:27], v[166:169], v[190:193], v[24:27]
	v_mfma_f32_16x16x32_bf16 v[12:15], v[158:161], v[198:201], v[12:15]
	v_mfma_f32_16x16x32_bf16 v[8:11], v[166:169], v[198:201], v[8:11]
	v_mfma_f32_16x16x32_bf16 v[52:55], v[202:205], v[170:173], v[52:55]
	v_mfma_f32_16x16x32_bf16 v[48:51], v[210:213], v[170:173], v[48:51]
	v_mfma_f32_16x16x32_bf16 v[36:39], v[202:205], v[178:181], v[36:39]
	v_mfma_f32_16x16x32_bf16 v[32:35], v[210:213], v[178:181], v[32:35]
	v_mfma_f32_16x16x32_bf16 v[20:23], v[202:205], v[186:189], v[20:23]
	v_mfma_f32_16x16x32_bf16 v[16:19], v[210:213], v[186:189], v[16:19]
	v_mfma_f32_16x16x32_bf16 v[4:7], v[202:205], v[194:197], v[4:7]
	v_mfma_f32_16x16x32_bf16 v[0:3], v[210:213], v[194:197], v[0:3]
	v_mfma_f32_16x16x32_bf16 v[52:55], v[206:209], v[174:177], v[52:55]
	v_mfma_f32_16x16x32_bf16 v[48:51], v[214:217], v[174:177], v[48:51]
	v_mfma_f32_16x16x32_bf16 v[36:39], v[206:209], v[182:185], v[36:39]
	v_mfma_f32_16x16x32_bf16 v[32:35], v[214:217], v[182:185], v[32:35]
	v_mfma_f32_16x16x32_bf16 v[20:23], v[206:209], v[190:193], v[20:23]
	v_mfma_f32_16x16x32_bf16 v[16:19], v[214:217], v[190:193], v[16:19]
	v_mfma_f32_16x16x32_bf16 v[4:7], v[206:209], v[198:201], v[4:7]
	v_mfma_f32_16x16x32_bf16 v[0:3], v[214:217], v[198:201], v[0:3]
	s_nop 0
	s_add_i32 s33, s33, 2
	s_add_u32 s62, s62, 0x100
	s_addc_u32 s63, s63, 0
	s_add_u32 s9, s9, 0x100
	s_addc_u32 s31, s31, 0
	s_cmp_gt_u32 s33, 13
	s_barrier
	s_cbranch_scc0 .LBB0_119
	v_lshl_or_b32 v146, s60, 8, v153
	v_cmp_lt_i32_e32 vcc, s80, v146
	s_and_saveexec_b64 s[60:61], vcc
	s_cbranch_execz .LBB0_122
	v_mul_f32_e32 v148, 0x3d372713, v125
	v_mul_f32_e32 v148, v125, v148
	v_fma_f32 v148, v125, v148, v125
	v_mul_f32_e32 v147, 0x3d372713, v124
	v_mul_f32_e32 v148, 0xbfcc422a, v148
	v_mul_f32_e32 v147, v124, v147
	v_mul_f32_e32 v148, 0x3fb8aa3b, v148
	v_fma_f32 v147, v124, v147, v124
	v_exp_f32_e32 v149, v148
	v_mul_f32_e32 v148, 0x3d372713, v126
	v_mul_f32_e32 v147, 0xbfcc422a, v147
	v_mul_f32_e32 v148, v126, v148
	v_mul_f32_e32 v147, 0x3fb8aa3b, v147
	v_fma_f32 v148, v126, v148, v126
	v_exp_f32_e32 v147, v147
	v_mul_f32_e32 v148, 0xbfcc422a, v148
	v_mul_f32_e32 v148, 0x3fb8aa3b, v148
	v_exp_f32_e32 v157, v148
	v_add_f32_e32 v147, 1.0, v147
	v_rcp_f32_e32 v148, v147
	v_add_f32_e32 v147, 1.0, v149
	v_rcp_f32_e32 v149, v147
	v_add_f32_e32 v147, 1.0, v157
	v_mul_f32_e32 v157, 0x3d372713, v127
	v_mul_f32_e32 v157, v127, v157
	v_mul_f32_e32 v158, 0x3d372713, v120
	v_fma_f32 v157, v127, v157, v127
	v_mul_f32_e32 v158, v120, v158
	v_mul_f32_e32 v157, 0xbfcc422a, v157
	v_fma_f32 v158, v120, v158, v120
	v_mul_f32_e32 v157, 0x3fb8aa3b, v157
	v_mul_f32_e32 v158, 0xbfcc422a, v158
	v_exp_f32_e32 v157, v157
	v_mul_f32_e32 v158, 0x3fb8aa3b, v158
	v_exp_f32_e32 v160, v158
	v_rcp_f32_e32 v158, v147
	v_add_f32_e32 v147, 1.0, v157
	v_rcp_f32_e32 v159, v147
	v_add_f32_e32 v147, 1.0, v160
	v_mul_f32_e32 v157, 0x3d372713, v122
	v_rcp_f32_e32 v160, v147
	v_mul_f32_e32 v147, 0x3d372713, v121
	v_mul_f32_e32 v157, v122, v157
	v_mul_f32_e32 v161, 0x3d372713, v123
	v_mul_f32_e32 v147, v121, v147
	v_fma_f32 v157, v122, v157, v122
	v_mul_f32_e32 v161, v123, v161
	v_fma_f32 v147, v121, v147, v121
	v_mul_f32_e32 v157, 0xbfcc422a, v157
	v_fma_f32 v161, v123, v161, v123
	v_mul_f32_e32 v147, 0xbfcc422a, v147
	v_mul_f32_e32 v157, 0x3fb8aa3b, v157
	v_mul_f32_e32 v161, 0xbfcc422a, v161
	v_mul_f32_e32 v147, 0x3fb8aa3b, v147
	v_exp_f32_e32 v157, v157
	v_mul_f32_e32 v161, 0x3fb8aa3b, v161
	v_exp_f32_e32 v147, v147
	v_exp_f32_e32 v161, v161
	v_add_f32_e32 v157, 1.0, v157
	v_rcp_f32_e32 v162, v157
	v_add_f32_e32 v147, 1.0, v147
	v_add_f32_e32 v157, 1.0, v161
	v_rcp_f32_e32 v163, v157
	v_rcp_f32_e32 v161, v147
	v_pk_mul_f32 v[126:127], v[126:127], v[158:159]
	v_pk_mul_f32 v[124:125], v[124:125], v[148:149]
	v_pk_mul_f32 v[122:123], v[122:123], v[162:163]
	v_pk_mul_f32 v[120:121], v[120:121], v[160:161]

; #define PG8_STAGE(bufoff, gbase, voff) do { _Pragma("unroll") for (int _i = 0; _i < 2; ++_i) \
;         __builtin_amdgcn_global_load_lds((const unsigned*)((const char*)(gbase) + (voff)[_i]), (LAS unsigned*)(lds + (bufoff) + ldsw + _i * 8192), 16, 0, 0); } while (0)
; #define PG8_LDA(dst, b, h) do { _Pragma("unroll") for (int m = 0; m < 4; ++m) _Pragma("unroll") for (int k = 0; k < 2; ++k) dst[m][k] = *(const LAS bf16x8*)(lds + PG8_SA(b, h) + aoff + m * 2048 + k * 1024); } while (0)
; #define PG8_LDB(dst, b, h) do { _Pragma("unroll") for (int n = 0; n < 2; ++n) _Pragma("unroll") for (int k = 0; k < 2; ++k) dst[n][k] = *(const LAS bf16x8*)(lds + PG8_SB(b, h) + boff + n * 2048 + k * 1024); } while (0)
; #define PG8_MMA(ai, bj, At, Bt) do { __builtin_amdgcn_s_setprio(1); _Pragma("unroll") for (int m = 0; m < 4; ++m) _Pragma("unroll") for (int n = 0; n < 2; ++n) _Pragma("unroll") for (int k = 0; k < 2; ++k) \
;         acc[ai][bj][m][n] = __builtin_amdgcn_mfma_f32_16x16x32_bf16(Bt[n][k], At[m][k], acc[ai][bj][m][n], 0, 0, 0); __builtin_amdgcn_s_setprio(0); } while (0)
; #define PG8_WAIT_V(n) asm volatile("s_waitcnt vmcnt(" #n ")" ::: "memory")
; #define PG8_WAIT_L(n) asm volatile("s_waitcnt lgkmcnt(" #n ")" ::: "memory")
; template <class Epi>
; __device__ __forceinline__ void gemm_phase(LAS unsigned char* lds, const Gemm g, const StaticOrder& S, const Epi& E) {
;     ...
;         for (int t = 0; t < nt; t += 2) {
;             const bool last = (t == nt - 2);
;             const char* a1 = cA + (size_t)(t + 1) * kstep;
;             const char* a2 = last ? nA : cA + (size_t)(t + 2) * kstep; const char* b2 = last ? nB : cB + (size_t)(t + 2) * kstep;
;             const char* a3 = a2 + kstep; const char* b3 = b2 + kstep;
;             PG8_LDB(B0, 0, 0); PG8_SCHED; PG8_LDA(At, 0, 0); PG8_STAGE(PG8_SA(1, 1), a1 + hstepA, voffA);
;             PG8_WAIT_L(8); PG8_BAR; PG8_WAIT_L(0); PG8_MMA(0, 0, At, B0); PG8_BAR; PG8_SCHED;
;             PG8_LDB(B1, 0, 1); PG8_STAGE(PG8_SB(0, 0), b2, voffB);
;             PG8_BAR; PG8_WAIT_L(0); PG8_MMA(0, 1, At, B1); PG8_BAR;
;             PG8_LDA(At, 0, 1); PG8_STAGE(PG8_SA(0, 0), a2, voffA);
;             PG8_BAR; PG8_WAIT_L(0); PG8_MMA(1, 0, At, B0); PG8_BAR; PG8_SCHED;
;             PG8_STAGE(PG8_SB(0, 1), b2 + hstepB, voffB);
;             PG8_WAIT_V(6); PG8_BAR; PG8_MMA(1, 1, At, B1); PG8_BAR;
.LBB0_456:
	ds_read_b128 v[144:147], v158
	ds_read_b128 v[148:151], v158 offset:1024
	ds_read_b128 v[162:165], v158 offset:2048
	ds_read_b128 v[166:169], v158 offset:3072
	s_add_i32 s85, s59, 2
	s_add_u32 s66, s64, 0xfffc0080
	s_addc_u32 s67, s65, -1
	s_cmp_eq_u32 s21, s59
	s_cselect_b32 s69, s63, s67
	s_cselect_b32 s68, s62, s66
	s_cselect_b32 s67, s1, s57
	s_cselect_b32 s66, s0, s31
	v_lshl_add_u64 v[152:153], s[64:65], 0, v[138:139]
	s_add_i32 m0, s35, 0xc000
	ds_read_b128 v[170:173], v159
	ds_read_b128 v[174:177], v159 offset:1024
	ds_read_b128 v[178:181], v159 offset:2048
	ds_read_b128 v[182:185], v159 offset:3072
	ds_read_b128 v[186:189], v159 offset:4096
	ds_read_b128 v[190:193], v159 offset:5120
	ds_read_b128 v[194:197], v159 offset:6144
	ds_read_b128 v[198:201], v159 offset:7168
	global_load_lds_dwordx4 v[152:153], off
	v_lshl_add_u64 v[152:153], s[64:65], 0, v[140:141]
	s_add_i32 m0, s35, 0xe000
	s_nop 0
	global_load_lds_dwordx4 v[152:153], off
	ds_read_b128 v[202:205], v160
	ds_read_b128 v[206:209], v160 offset:1024
	ds_read_b128 v[210:213], v160 offset:2048
	ds_read_b128 v[214:217], v160 offset:3072
	s_waitcnt vmcnt(8) lgkmcnt(0)
	s_barrier
	s_nop 0
	v_mfma_f32_16x16x32_bf16 v[124:127], v[144:147], v[170:173], v[124:127]
	v_mfma_f32_16x16x32_bf16 v[120:123], v[162:165], v[170:173], v[120:123]
	v_mfma_f32_16x16x32_bf16 v[116:119], v[144:147], v[178:181], v[116:119]
	v_mfma_f32_16x16x32_bf16 v[108:111], v[162:165], v[178:181], v[108:111]
	v_mfma_f32_16x16x32_bf16 v[100:103], v[144:147], v[186:189], v[100:103]
	v_mfma_f32_16x16x32_bf16 v[92:95], v[162:165], v[186:189], v[92:95]
	v_mfma_f32_16x16x32_bf16 v[84:87], v[144:147], v[194:197], v[84:87]
	v_mfma_f32_16x16x32_bf16 v[76:79], v[162:165], v[194:197], v[76:79]
	v_mfma_f32_16x16x32_bf16 v[124:127], v[148:151], v[174:177], v[124:127]
	v_mfma_f32_16x16x32_bf16 v[120:123], v[166:169], v[174:177], v[120:123]
	v_mfma_f32_16x16x32_bf16 v[116:119], v[148:151], v[182:185], v[116:119]
	v_mfma_f32_16x16x32_bf16 v[108:111], v[166:169], v[182:185], v[108:111]
	v_mfma_f32_16x16x32_bf16 v[100:103], v[148:151], v[190:193], v[100:103]
	v_mfma_f32_16x16x32_bf16 v[92:95], v[166:169], v[190:193], v[92:95]
	v_mfma_f32_16x16x32_bf16 v[84:87], v[148:151], v[198:201], v[84:87]
	v_mfma_f32_16x16x32_bf16 v[76:79], v[166:169], v[198:201], v[76:79]
	v_mfma_f32_16x16x32_bf16 v[112:115], v[202:205], v[170:173], v[112:115]
	v_mfma_f32_16x16x32_bf16 v[104:107], v[210:213], v[170:173], v[104:107]
	v_mfma_f32_16x16x32_bf16 v[96:99], v[202:205], v[178:181], v[96:99]
	v_mfma_f32_16x16x32_bf16 v[88:91], v[210:213], v[178:181], v[88:91]
	v_mfma_f32_16x16x32_bf16 v[80:83], v[202:205], v[186:189], v[80:83]
	v_mfma_f32_16x16x32_bf16 v[72:75], v[210:213], v[186:189], v[72:75]
	v_mfma_f32_16x16x32_bf16 v[68:71], v[202:205], v[194:197], v[68:71]
	v_mfma_f32_16x16x32_bf16 v[64:67], v[210:213], v[194:197], v[64:67]
	v_mfma_f32_16x16x32_bf16 v[112:115], v[206:209], v[174:177], v[112:115]
	v_mfma_f32_16x16x32_bf16 v[104:107], v[214:217], v[174:177], v[104:107]
	v_mfma_f32_16x16x32_bf16 v[96:99], v[206:209], v[182:185], v[96:99]
	v_mfma_f32_16x16x32_bf16 v[88:91], v[214:217], v[182:185], v[88:91]
	v_mfma_f32_16x16x32_bf16 v[80:83], v[206:209], v[190:193], v[80:83]
	v_mfma_f32_16x16x32_bf16 v[72:75], v[214:217], v[190:193], v[72:75]
	v_mfma_f32_16x16x32_bf16 v[68:71], v[206:209], v[198:201], v[68:71]
	v_mfma_f32_16x16x32_bf16 v[64:67], v[214:217], v[198:201], v[64:67]
	s_nop 0
	s_barrier
	s_add_i32 s59, s78, s33
	v_lshl_add_u64 v[152:153], s[66:67], 0, v[132:133]
	s_mov_b32 m0, s59
	global_load_lds_dwordx4 v[152:153], off
	v_lshl_add_u64 v[218:219], s[66:67], 0, v[136:137]
	s_add_i32 m0, s59, 0x2000
	s_nop 0
	global_load_lds_dwordx4 v[218:219], off
	s_mov_b32 m0, s35
	v_lshl_add_u64 v[220:221], s[68:69], 0, v[130:131]
	ds_read_b128 v[170:173], v159 offset:16384
	ds_read_b128 v[174:177], v159 offset:17408
	ds_read_b128 v[178:181], v159 offset:18432
	ds_read_b128 v[182:185], v159 offset:19456
	ds_read_b128 v[186:189], v159 offset:20480
	ds_read_b128 v[190:193], v159 offset:21504
	ds_read_b128 v[194:197], v159 offset:22528
	ds_read_b128 v[198:201], v159 offset:23552
	global_load_lds_dwordx4 v[220:221], off
	v_lshl_add_u64 v[222:223], s[68:69], 0, v[134:135]
	s_mov_b32 m0, s70
	s_nop 0
	global_load_lds_dwordx4 v[222:223], off
	s_add_u32 s86, s66, 0x40000
	s_addc_u32 s87, s67, 0
	s_add_i32 s59, s79, s33
	v_lshl_add_u64 v[240:241], s[86:87], 0, v[132:133]
	s_mov_b32 m0, s59
	s_nop 0
	global_load_lds_dwordx4 v[240:241], off
	v_lshl_add_u64 v[240:241], s[86:87], 0, v[136:137]
	s_add_i32 m0, s59, 0x2000
	s_nop 0
	global_load_lds_dwordx4 v[240:241], off
	s_waitcnt vmcnt(8) lgkmcnt(0)
	s_barrier
; #define PG8_STAGE(bufoff, gbase, voff) do { _Pragma("unroll") for (int _i = 0; _i < 2; ++_i) \
;         __builtin_amdgcn_global_load_lds((const unsigned*)((const char*)(gbase) + (voff)[_i]), (LAS unsigned*)(lds + (bufoff) + ldsw + _i * 8192), 16, 0, 0); } while (0)
; #define PG8_LDA(dst, b, h) do { _Pragma("unroll") for (int m = 0; m < 4; ++m) _Pragma("unroll") for (int k = 0; k < 2; ++k) dst[m][k] = *(const LAS bf16x8*)(lds + PG8_SA(b, h) + aoff + m * 2048 + k * 1024); } while (0)
; #define PG8_LDB(dst, b, h) do { _Pragma("unroll") for (int n = 0; n < 2; ++n) _Pragma("unroll") for (int k = 0; k < 2; ++k) dst[n][k] = *(const LAS bf16x8*)(lds + PG8_SB(b, h) + boff + n * 2048 + k * 1024); } while (0)
; #define PG8_WAIT_V(n) asm volatile("s_waitcnt vmcnt(" #n ")" ::: "memory")
; #define PG8_WAIT_L(n) asm volatile("s_waitcnt lgkmcnt(" #n ")" ::: "memory")
; #define PG8_BAR __builtin_amdgcn_s_barrier()
; #define PG8_SCHED __builtin_amdgcn_sched_barrier(0)
; template <class Epi>
; __device__ __forceinline__ void gemm_phase(LAS unsigned char* lds, const Gemm g, const StaticOrder& S, const Epi& E) {
;     ...
;             PG8_LDB(B0, 0, 0); PG8_SCHED; PG8_LDA(At, 0, 0); PG8_STAGE(PG8_SA(1, 1), a1 + hstepA, voffA);
;             PG8_WAIT_L(8); PG8_BAR; PG8_WAIT_L(0); PG8_MMA(0, 0, At, B0); PG8_BAR; PG8_SCHED;
;             PG8_LDB(B1, 0, 1); PG8_STAGE(PG8_SB(0, 0), b2, voffB);
;             PG8_BAR; PG8_WAIT_L(0); PG8_MMA(0, 1, At, B1); PG8_BAR;
;             PG8_LDA(At, 0, 1); PG8_STAGE(PG8_SA(0, 0), a2, voffA);
;             PG8_BAR; PG8_WAIT_L(0); PG8_MMA(1, 0, At, B0); PG8_BAR; PG8_SCHED;
;             PG8_STAGE(PG8_SB(0, 1), b2 + hstepB, voffB);
;             PG8_WAIT_V(6); PG8_BAR; PG8_MMA(1, 1, At, B1); PG8_BAR;
;             PG8_LDB(B0, 1, 0); PG8_SCHED; PG8_LDA(At, 1, 0); PG8_STAGE(PG8_SA(0, 1), a2 + hstepA, voffA);
;             PG8_WAIT_L(8); PG8_BAR; PG8_WAIT_L(0); PG8_MMA(0, 0, At, B0); PG8_BAR; PG8_SCHED;
;             PG8_LDB(B1, 1, 1); PG8_STAGE(PG8_SB(1, 0), b3, voffB);
;             PG8_BAR; PG8_WAIT_L(0); PG8_MMA(0, 1, At, B1); PG8_BAR;
;             PG8_LDA(At, 1, 1); PG8_STAGE(PG8_SA(1, 0), a3, voffA);
;             PG8_BAR; PG8_WAIT_L(0); PG8_MMA(1, 0, At, B0); PG8_BAR; PG8_SCHED;
;             PG8_STAGE(PG8_SB(1, 1), b3 + hstepB, voffB);
;             PG8_WAIT_V(6); PG8_BAR; PG8_MMA(1, 1, At, B1); PG8_BAR;
	s_nop 0
	v_mfma_f32_16x16x32_bf16 v[60:63], v[144:147], v[170:173], v[60:63]
	v_mfma_f32_16x16x32_bf16 v[56:59], v[162:165], v[170:173], v[56:59]
	v_mfma_f32_16x16x32_bf16 v[52:55], v[144:147], v[178:181], v[52:55]
	v_mfma_f32_16x16x32_bf16 v[44:47], v[162:165], v[178:181], v[44:47]
	v_mfma_f32_16x16x32_bf16 v[36:39], v[144:147], v[186:189], v[36:39]
	v_mfma_f32_16x16x32_bf16 v[28:31], v[162:165], v[186:189], v[28:31]
	v_mfma_f32_16x16x32_bf16 v[20:23], v[144:147], v[194:197], v[20:23]
	v_mfma_f32_16x16x32_bf16 v[12:15], v[162:165], v[194:197], v[12:15]
	v_mfma_f32_16x16x32_bf16 v[60:63], v[148:151], v[174:177], v[60:63]
	v_mfma_f32_16x16x32_bf16 v[56:59], v[166:169], v[174:177], v[56:59]
	v_mfma_f32_16x16x32_bf16 v[52:55], v[148:151], v[182:185], v[52:55]
	v_mfma_f32_16x16x32_bf16 v[44:47], v[166:169], v[182:185], v[44:47]
	v_mfma_f32_16x16x32_bf16 v[36:39], v[148:151], v[190:193], v[36:39]
	v_mfma_f32_16x16x32_bf16 v[28:31], v[166:169], v[190:193], v[28:31]
	v_mfma_f32_16x16x32_bf16 v[20:23], v[148:151], v[198:201], v[20:23]
	v_mfma_f32_16x16x32_bf16 v[12:15], v[166:169], v[198:201], v[12:15]
	v_mfma_f32_16x16x32_bf16 v[48:51], v[202:205], v[170:173], v[48:51]
	v_mfma_f32_16x16x32_bf16 v[40:43], v[210:213], v[170:173], v[40:43]
	v_mfma_f32_16x16x32_bf16 v[32:35], v[202:205], v[178:181], v[32:35]
	v_mfma_f32_16x16x32_bf16 v[24:27], v[210:213], v[178:181], v[24:27]
	v_mfma_f32_16x16x32_bf16 v[16:19], v[202:205], v[186:189], v[16:19]
	v_mfma_f32_16x16x32_bf16 v[8:11], v[210:213], v[186:189], v[8:11]
	v_mfma_f32_16x16x32_bf16 v[4:7], v[202:205], v[194:197], v[4:7]
	v_mfma_f32_16x16x32_bf16 v[0:3], v[210:213], v[194:197], v[0:3]
	v_mfma_f32_16x16x32_bf16 v[48:51], v[206:209], v[174:177], v[48:51]
	v_mfma_f32_16x16x32_bf16 v[40:43], v[214:217], v[174:177], v[40:43]
	v_mfma_f32_16x16x32_bf16 v[32:35], v[206:209], v[182:185], v[32:35]
	v_mfma_f32_16x16x32_bf16 v[24:27], v[214:217], v[182:185], v[24:27]
	v_mfma_f32_16x16x32_bf16 v[16:19], v[206:209], v[190:193], v[16:19]
	v_mfma_f32_16x16x32_bf16 v[8:11], v[214:217], v[190:193], v[8:11]
	v_mfma_f32_16x16x32_bf16 v[4:7], v[206:209], v[198:201], v[4:7]
	v_mfma_f32_16x16x32_bf16 v[0:3], v[214:217], v[198:201], v[0:3]
	s_nop 0
	s_barrier
	s_add_i32 s59, 0, 0x18000
	v_add_u32_e32 v161, s59, v156
	ds_read_b128 v[144:147], v161
	ds_read_b128 v[148:151], v161 offset:1024
	ds_read_b128 v[162:165], v161 offset:2048
	ds_read_b128 v[166:169], v161 offset:3072
	s_add_u32 s68, s68, 0x40000
	s_addc_u32 s69, s69, 0
	s_mov_b32 m0, s71
	v_lshl_add_u64 v[202:203], s[68:69], 0, v[130:131]
	ds_read_b128 v[170:173], v159 offset:32768
	ds_read_b128 v[174:177], v159 offset:33792
	ds_read_b128 v[178:181], v159 offset:34816
	ds_read_b128 v[182:185], v159 offset:35840
	ds_read_b128 v[186:189], v159 offset:36864
	ds_read_b128 v[190:193], v159 offset:37888
	ds_read_b128 v[194:197], v159 offset:38912
	ds_read_b128 v[198:201], v159 offset:39936
	global_load_lds_dwordx4 v[202:203], off
	v_lshl_add_u64 v[202:203], s[68:69], 0, v[134:135]
	s_mov_b32 m0, s72
	s_nop 0
	global_load_lds_dwordx4 v[202:203], off
	s_add_i32 s68, 0, 0x1c000
	v_add_u32_e32 v161, s68, v156
	ds_read_b128 v[202:205], v161
	ds_read_b128 v[206:209], v161 offset:1024
	ds_read_b128 v[210:213], v161 offset:2048
	ds_read_b128 v[214:217], v161 offset:3072
	s_waitcnt vmcnt(8) lgkmcnt(0)
	s_barrier
	s_nop 0
	v_mfma_f32_16x16x32_bf16 v[124:127], v[144:147], v[170:173], v[124:127]
	v_mfma_f32_16x16x32_bf16 v[120:123], v[162:165], v[170:173], v[120:123]
	v_mfma_f32_16x16x32_bf16 v[116:119], v[144:147], v[178:181], v[116:119]
	v_mfma_f32_16x16x32_bf16 v[108:111], v[162:165], v[178:181], v[108:111]
	v_mfma_f32_16x16x32_bf16 v[100:103], v[144:147], v[186:189], v[100:103]
	v_mfma_f32_16x16x32_bf16 v[92:95], v[162:165], v[186:189], v[92:95]
	v_mfma_f32_16x16x32_bf16 v[84:87], v[144:147], v[194:197], v[84:87]
	v_mfma_f32_16x16x32_bf16 v[76:79], v[162:165], v[194:197], v[76:79]
	v_mfma_f32_16x16x32_bf16 v[124:127], v[148:151], v[174:177], v[124:127]
	v_mfma_f32_16x16x32_bf16 v[120:123], v[166:169], v[174:177], v[120:123]
	v_mfma_f32_16x16x32_bf16 v[116:119], v[148:151], v[182:185], v[116:119]
	v_mfma_f32_16x16x32_bf16 v[108:111], v[166:169], v[182:185], v[108:111]
	v_mfma_f32_16x16x32_bf16 v[100:103], v[148:151], v[190:193], v[100:103]
	v_mfma_f32_16x16x32_bf16 v[92:95], v[166:169], v[190:193], v[92:95]
	v_mfma_f32_16x16x32_bf16 v[84:87], v[148:151], v[198:201], v[84:87]
	v_mfma_f32_16x16x32_bf16 v[76:79], v[166:169], v[198:201], v[76:79]
	v_mfma_f32_16x16x32_bf16 v[112:115], v[202:205], v[170:173], v[112:115]
	v_mfma_f32_16x16x32_bf16 v[104:107], v[210:213], v[170:173], v[104:107]
	v_mfma_f32_16x16x32_bf16 v[96:99], v[202:205], v[178:181], v[96:99]
	v_mfma_f32_16x16x32_bf16 v[88:91], v[210:213], v[178:181], v[88:91]
	v_mfma_f32_16x16x32_bf16 v[80:83], v[202:205], v[186:189], v[80:83]
	v_mfma_f32_16x16x32_bf16 v[72:75], v[210:213], v[186:189], v[72:75]
	v_mfma_f32_16x16x32_bf16 v[68:71], v[202:205], v[194:197], v[68:71]
	v_mfma_f32_16x16x32_bf16 v[64:67], v[210:213], v[194:197], v[64:67]
	v_mfma_f32_16x16x32_bf16 v[112:115], v[206:209], v[174:177], v[112:115]
	v_mfma_f32_16x16x32_bf16 v[104:107], v[214:217], v[174:177], v[104:107]
	v_mfma_f32_16x16x32_bf16 v[96:99], v[206:209], v[182:185], v[96:99]
	v_mfma_f32_16x16x32_bf16 v[88:91], v[214:217], v[182:185], v[88:91]
	v_mfma_f32_16x16x32_bf16 v[80:83], v[206:209], v[190:193], v[80:83]
	v_mfma_f32_16x16x32_bf16 v[72:75], v[214:217], v[190:193], v[72:75]
	v_mfma_f32_16x16x32_bf16 v[68:71], v[206:209], v[198:201], v[68:71]
	v_mfma_f32_16x16x32_bf16 v[64:67], v[214:217], v[198:201], v[64:67]
	s_nop 0
	s_barrier
; #define PG8_STAGE(bufoff, gbase, voff) do { _Pragma("unroll") for (int _i = 0; _i < 2; ++_i) \
;         __builtin_amdgcn_global_load_lds((const unsigned*)((const char*)(gbase) + (voff)[_i]), (LAS unsigned*)(lds + (bufoff) + ldsw + _i * 8192), 16, 0, 0); } while (0)
; #define PG8_LDA(dst, b, h) do { _Pragma("unroll") for (int m = 0; m < 4; ++m) _Pragma("unroll") for (int k = 0; k < 2; ++k) dst[m][k] = *(const LAS bf16x8*)(lds + PG8_SA(b, h) + aoff + m * 2048 + k * 1024); } while (0)
; #define PG8_MMA(ai, bj, At, Bt) do { __builtin_amdgcn_s_setprio(1); _Pragma("unroll") for (int m = 0; m < 4; ++m) _Pragma("unroll") for (int n = 0; n < 2; ++n) _Pragma("unroll") for (int k = 0; k < 2; ++k) \
;         acc[ai][bj][m][n] = __builtin_amdgcn_mfma_f32_16x16x32_bf16(Bt[n][k], At[m][k], acc[ai][bj][m][n], 0, 0, 0); __builtin_amdgcn_s_setprio(0); } while (0)
; #define PG8_WAIT_V(n) asm volatile("s_waitcnt vmcnt(" #n ")" ::: "memory")
; #define PG8_WAIT_L(n) asm volatile("s_waitcnt lgkmcnt(" #n ")" ::: "memory")
; #define PG8_BAR __builtin_amdgcn_s_barrier()
; #define PG8_SCHED __builtin_amdgcn_sched_barrier(0)
; template <class Epi>
; __device__ __forceinline__ void gemm_phase(LAS unsigned char* lds, const Gemm g, const StaticOrder& S, const Epi& E) {
;     ...
;         for (int t = 0; t < nt; t += 2) {
;     ...
;             PG8_LDA(At, 1, 1); PG8_STAGE(PG8_SA(1, 0), a3, voffA);
;             PG8_BAR; PG8_WAIT_L(0); PG8_MMA(1, 0, At, B0); PG8_BAR; PG8_SCHED;
;             PG8_STAGE(PG8_SB(1, 1), b3 + hstepB, voffB);
;             PG8_WAIT_V(6); PG8_BAR; PG8_MMA(1, 1, At, B1); PG8_BAR;
	s_add_i32 s59, s59, s33
	v_lshl_add_u64 v[152:153], v[152:153], 0, s[12:13]
	s_mov_b32 m0, s59
	global_load_lds_dwordx4 v[152:153], off
	v_lshl_add_u64 v[152:153], v[218:219], 0, s[12:13]
	s_add_i32 m0, s59, 0x2000
	s_nop 0
	global_load_lds_dwordx4 v[152:153], off
	s_mov_b32 m0, s73
	v_lshl_add_u64 v[152:153], v[220:221], 0, s[12:13]
	ds_read_b128 v[170:173], v159 offset:49152
	ds_read_b128 v[174:177], v159 offset:50176
	ds_read_b128 v[178:181], v159 offset:51200
	ds_read_b128 v[182:185], v159 offset:52224
	ds_read_b128 v[186:189], v159 offset:53248
	ds_read_b128 v[190:193], v159 offset:54272
	ds_read_b128 v[194:197], v159 offset:55296
	ds_read_b128 v[198:201], v159 offset:56320
	global_load_lds_dwordx4 v[152:153], off
	v_lshl_add_u64 v[152:153], v[222:223], 0, s[12:13]
	s_mov_b32 m0, s74
	s_nop 0
	global_load_lds_dwordx4 v[152:153], off
	s_add_u32 s66, s66, 0x40080
	s_addc_u32 s67, s67, 0
	s_add_i32 s59, s68, s33
	v_lshl_add_u64 v[240:241], s[66:67], 0, v[132:133]
	s_mov_b32 m0, s59
	s_nop 0
	global_load_lds_dwordx4 v[240:241], off
	v_lshl_add_u64 v[240:241], s[66:67], 0, v[136:137]
	s_add_i32 m0, s59, 0x2000
	s_nop 0
	global_load_lds_dwordx4 v[240:241], off
	s_waitcnt vmcnt(8) lgkmcnt(0)
	s_barrier
	s_nop 0
	v_mfma_f32_16x16x32_bf16 v[60:63], v[144:147], v[170:173], v[60:63]
	v_mfma_f32_16x16x32_bf16 v[56:59], v[162:165], v[170:173], v[56:59]
	v_mfma_f32_16x16x32_bf16 v[52:55], v[144:147], v[178:181], v[52:55]
	v_mfma_f32_16x16x32_bf16 v[44:47], v[162:165], v[178:181], v[44:47]
	v_mfma_f32_16x16x32_bf16 v[36:39], v[144:147], v[186:189], v[36:39]
	v_mfma_f32_16x16x32_bf16 v[28:31], v[162:165], v[186:189], v[28:31]
	v_mfma_f32_16x16x32_bf16 v[20:23], v[144:147], v[194:197], v[20:23]
	v_mfma_f32_16x16x32_bf16 v[12:15], v[162:165], v[194:197], v[12:15]
	v_mfma_f32_16x16x32_bf16 v[60:63], v[148:151], v[174:177], v[60:63]
	v_mfma_f32_16x16x32_bf16 v[56:59], v[166:169], v[174:177], v[56:59]
	v_mfma_f32_16x16x32_bf16 v[52:55], v[148:151], v[182:185], v[52:55]
	v_mfma_f32_16x16x32_bf16 v[44:47], v[166:169], v[182:185], v[44:47]
	v_mfma_f32_16x16x32_bf16 v[36:39], v[148:151], v[190:193], v[36:39]
	v_mfma_f32_16x16x32_bf16 v[28:31], v[166:169], v[190:193], v[28:31]
	v_mfma_f32_16x16x32_bf16 v[20:23], v[148:151], v[198:201], v[20:23]
	v_mfma_f32_16x16x32_bf16 v[12:15], v[166:169], v[198:201], v[12:15]
	v_mfma_f32_16x16x32_bf16 v[48:51], v[202:205], v[170:173], v[48:51]
	v_mfma_f32_16x16x32_bf16 v[40:43], v[210:213], v[170:173], v[40:43]
	v_mfma_f32_16x16x32_bf16 v[32:35], v[202:205], v[178:181], v[32:35]
	v_mfma_f32_16x16x32_bf16 v[24:27], v[210:213], v[178:181], v[24:27]
	v_mfma_f32_16x16x32_bf16 v[16:19], v[202:205], v[186:189], v[16:19]
	v_mfma_f32_16x16x32_bf16 v[8:11], v[210:213], v[186:189], v[8:11]
	v_mfma_f32_16x16x32_bf16 v[4:7], v[202:205], v[194:197], v[4:7]
	v_mfma_f32_16x16x32_bf16 v[0:3], v[210:213], v[194:197], v[0:3]
	v_mfma_f32_16x16x32_bf16 v[48:51], v[206:209], v[174:177], v[48:51]
	v_mfma_f32_16x16x32_bf16 v[40:43], v[214:217], v[174:177], v[40:43]
	v_mfma_f32_16x16x32_bf16 v[32:35], v[206:209], v[182:185], v[32:35]
	v_mfma_f32_16x16x32_bf16 v[24:27], v[214:217], v[182:185], v[24:27]
	v_mfma_f32_16x16x32_bf16 v[16:19], v[206:209], v[190:193], v[16:19]
	v_mfma_f32_16x16x32_bf16 v[8:11], v[214:217], v[190:193], v[8:11]
	v_mfma_f32_16x16x32_bf16 v[4:7], v[206:209], v[198:201], v[4:7]
	v_mfma_f32_16x16x32_bf16 v[0:3], v[214:217], v[198:201], v[0:3]
	s_nop 0
	s_add_u32 s64, s64, 0x100
	s_addc_u32 s65, s65, 0
	s_add_u32 s31, s31, 0x100
	s_addc_u32 s57, s57, 0
	s_cmp_ge_i32 s85, s84
	s_mov_b32 s59, s85
	s_barrier
	s_cbranch_scc0 .LBB0_456
;     __device__ __forceinline__ void operator()(const f32x4 (&acc)[2][2][4][2], const Unit& u, int wr, int wc, int fr, int fq) const {
;         const int row0 = u.pm * BM + wr * 64 + fr, col0 = u.pn * BM + wc * 32 + 8 * fq;
;         if (u.part) {
;             float* base = tailacc + (size_t)(u.part - 1) * slab - (size_t)tail_row0 * tail_ld;
; #pragma unroll
;             for (int ai = 0; ai < 2; ++ai)
; #pragma unroll
;                 for (int m = 0; m < 4; ++m) { float* rowp = base + (size_t)(row0 + ai * HALF + m * 16) * tail_ld + col0;
; #pragma unroll
;                     for (int bj = 0; bj < 2; ++bj)
; #pragma unroll
;                         for (int n = 0; n < 2; ++n) *(f32x4*)(rowp + bj * HALF + 4 * n) = acc[ai][bj][m][n]; }
	v_lshl_add_u32 v152, s8, 8, v155
	v_lshl_or_b32 v144, s30, 8, v157
	v_or_b32_e32 v150, 16, v152
	v_or_b32_e32 v148, 32, v152
	v_or_b32_e32 v146, 48, v152
	s_cmp_lg_u32 s81, 0
	v_ashrrev_i32_e32 v145, 31, v144
	v_ashrrev_i32_e32 v153, 31, v152
	v_ashrrev_i32_e32 v151, 31, v150
	v_ashrrev_i32_e32 v149, 31, v148
	v_ashrrev_i32_e32 v147, 31, v146
	s_cbranch_scc0 .LBB0_459
	s_add_i32 s8, s81, -1
	s_lshl_b64 s[30:31], s[8:9], 21
	s_add_u32 s30, s4, s30
	s_addc_u32 s31, s5, s31
	v_lshl_add_u64 v[162:163], v[144:145], 2, s[30:31]
	s_brev_b32 s30, 63
	s_mov_b32 s31, -1
	v_lshl_add_u64 v[162:163], v[162:163], 0, s[30:31]
	v_lshlrev_b64 v[164:165], 12, v[152:153]
	v_lshlrev_b64 v[166:167], 12, v[150:151]
	v_lshl_add_u64 v[164:165], v[162:163], 0, v[164:165]
	v_lshl_add_u64 v[166:167], v[162:163], 0, v[166:167]
	global_store_dwordx4 v[164:165], v[124:127], off
	global_store_dwordx4 v[164:165], v[120:123], off offset:16
	global_store_dwordx4 v[164:165], v[112:115], off offset:512
	global_store_dwordx4 v[164:165], v[104:107], off offset:528
	global_store_dwordx4 v[166:167], v[116:119], off
	global_store_dwordx4 v[166:167], v[108:111], off offset:16
	global_store_dwordx4 v[166:167], v[96:99], off offset:512
	global_store_dwordx4 v[166:167], v[88:91], off offset:528
	v_lshlrev_b64 v[166:167], 12, v[148:149]
	v_lshl_add_u64 v[166:167], v[162:163], 0, v[166:167]
	global_store_dwordx4 v[166:167], v[100:103], off
	global_store_dwordx4 v[166:167], v[92:95], off offset:16
	global_store_dwordx4 v[166:167], v[80:83], off offset:512
	global_store_dwordx4 v[166:167], v[72:75], off offset:528
	v_lshlrev_b64 v[166:167], 12, v[146:147]
	s_mov_b32 s8, 0x80000
	v_lshl_add_u64 v[162:163], v[162:163], 0, v[166:167]
	v_add_co_u32_e32 v166, vcc, s8, v164
	s_mov_b64 s[30:31], 0x80000
	s_nop 0
	v_addc_co_u32_e32 v167, vcc, 0, v165, vcc
	s_mov_b32 s8, 0x90000
	global_store_dwordx4 v[162:163], v[84:87], off
	global_store_dwordx4 v[162:163], v[76:79], off offset:16
	global_store_dwordx4 v[162:163], v[68:71], off offset:512
	global_store_dwordx4 v[162:163], v[64:67], off offset:528
	v_lshl_add_u64 v[162:163], v[164:165], 0, s[30:31]
	global_store_dwordx4 v[166:167], v[60:63], off
	global_store_dwordx4 v[162:163], v[56:59], off offset:16
	global_store_dwordx4 v[162:163], v[48:51], off offset:512
	global_store_dwordx4 v[162:163], v[40:43], off offset:528
	v_add_co_u32_e32 v166, vcc, s8, v164
	s_mov_b64 s[30:31], 0x90000
	s_nop 0
	v_addc_co_u32_e32 v167, vcc, 0, v165, vcc
	s_mov_b32 s8, 0xa0000
	v_lshl_add_u64 v[162:163], v[164:165], 0, s[30:31]
	global_store_dwordx4 v[166:167], v[52:55], off
	global_store_dwordx4 v[162:163], v[44:47], off offset:16
	global_store_dwordx4 v[162:163], v[32:35], off offset:512
	global_store_dwordx4 v[162:163], v[24:27], off offset:528
	s_mov_b64 s[30:31], 0xa0000
	v_add_co_u32_e32 v166, vcc, s8, v164
	v_lshl_add_u64 v[162:163], v[164:165], 0, s[30:31]
	s_nop 0
	v_addc_co_u32_e32 v167, vcc, 0, v165, vcc
	s_mov_b64 s[30:31], 0xb0000
	global_store_dwordx4 v[166:167], v[36:39], off
	global_store_dwordx4 v[162:163], v[28:31], off offset:16
	global_store_dwordx4 v[162:163], v[16:19], off offset:512
	global_store_dwordx4 v[162:163], v[8:11], off offset:528
	v_lshl_add_u64 v[162:163], v[164:165], 0, s[30:31]
	v_add_co_u32_e32 v164, vcc, 0xb0000, v164
	s_nop 1
	v_addc_co_u32_e32 v165, vcc, 0, v165, vcc
	global_store_dwordx4 v[164:165], v[20:23], off
	global_store_dwordx4 v[162:163], v[12:15], off offset:16
	global_store_dwordx4 v[162:163], v[4:7], off offset:512
	global_store_dwordx4 v[162:163], v[0:3], off offset:528
	s_cbranch_execnz .LBB0_441
	s_branch .LBB0_440

; #define PG8_STAGE(bufoff, gbase, voff) do { _Pragma("unroll") for (int _i = 0; _i < 2; ++_i) \
;         __builtin_amdgcn_global_load_lds((const unsigned*)((const char*)(gbase) + (voff)[_i]), (LAS unsigned*)(lds + (bufoff) + ldsw + _i * 8192), 16, 0, 0); } while (0)
; #define PG8_LDA(dst, b, h) do { _Pragma("unroll") for (int m = 0; m < 4; ++m) _Pragma("unroll") for (int k = 0; k < 2; ++k) dst[m][k] = *(const LAS bf16x8*)(lds + PG8_SA(b, h) + aoff + m * 2048 + k * 1024); } while (0)
; #define PG8_LDB(dst, b, h) do { _Pragma("unroll") for (int n = 0; n < 2; ++n) _Pragma("unroll") for (int k = 0; k < 2; ++k) dst[n][k] = *(const LAS bf16x8*)(lds + PG8_SB(b, h) + boff + n * 2048 + k * 1024); } while (0)
; #define PG8_MMA(ai, bj, At, Bt) do { __builtin_amdgcn_s_setprio(1); _Pragma("unroll") for (int m = 0; m < 4; ++m) _Pragma("unroll") for (int n = 0; n < 2; ++n) _Pragma("unroll") for (int k = 0; k < 2; ++k) \
;         acc[ai][bj][m][n] = __builtin_amdgcn_mfma_f32_16x16x32_bf16(Bt[n][k], At[m][k], acc[ai][bj][m][n], 0, 0, 0); __builtin_amdgcn_s_setprio(0); } while (0)
; #define PG8_WAIT_V(n) asm volatile("s_waitcnt vmcnt(" #n ")" ::: "memory")
; #define PG8_WAIT_L(n) asm volatile("s_waitcnt lgkmcnt(" #n ")" ::: "memory")
; #define PG8_BAR __builtin_amdgcn_s_barrier()
; #define PG8_SCHED __builtin_amdgcn_sched_barrier(0)
; template <class Epi>
; __device__ __forceinline__ void gemm_phase(LAS unsigned char* lds, const Gemm g, const StaticOrder& S, const Epi& E) {
;     ...
;             PG8_LDB(B0, 0, 0); PG8_SCHED; PG8_LDA(At, 0, 0); PG8_STAGE(PG8_SA(1, 1), a1 + hstepA, voffA);
;             PG8_WAIT_L(8); PG8_BAR; PG8_WAIT_L(0); PG8_MMA(0, 0, At, B0); PG8_BAR; PG8_SCHED;
;             PG8_LDB(B1, 0, 1); PG8_STAGE(PG8_SB(0, 0), b2, voffB);
;             PG8_BAR; PG8_WAIT_L(0); PG8_MMA(0, 1, At, B1); PG8_BAR;
;             PG8_LDA(At, 0, 1); PG8_STAGE(PG8_SA(0, 0), a2, voffA);
;             PG8_BAR; PG8_WAIT_L(0); PG8_MMA(1, 0, At, B0); PG8_BAR; PG8_SCHED;
;             PG8_STAGE(PG8_SB(0, 1), b2 + hstepB, voffB);
;             PG8_WAIT_V(6); PG8_BAR; PG8_MMA(1, 1, At, B1); PG8_BAR;
.LBB0_682:
	ds_read_b128 v[152:155], v159
	ds_read_b128 v[162:165], v159 offset:1024
	ds_read_b128 v[166:169], v159 offset:2048
	ds_read_b128 v[170:173], v159 offset:3072
	s_add_u32 s62, s60, 0xfffc0080
	s_addc_u32 s63, s61, -1
	s_cmp_eq_u32 s78, 12
	s_cselect_b32 s65, s41, s63
	s_cselect_b32 s64, s40, s62
	s_cselect_b32 s63, s57, s39
	s_cselect_b32 s62, s56, s37
	v_lshl_add_u64 v[206:207], s[60:61], 0, v[144:145]
	s_add_i32 m0, s35, 0xc000
	ds_read_b128 v[174:177], v160
	ds_read_b128 v[178:181], v160 offset:1024
	ds_read_b128 v[182:185], v160 offset:2048
	ds_read_b128 v[186:189], v160 offset:3072
	ds_read_b128 v[190:193], v160 offset:4096
	ds_read_b128 v[194:197], v160 offset:5120
	ds_read_b128 v[198:201], v160 offset:6144
	ds_read_b128 v[202:205], v160 offset:7168
	global_load_lds_dwordx4 v[206:207], off
	v_lshl_add_u64 v[206:207], s[60:61], 0, v[146:147]
	s_add_i32 m0, s35, 0xe000
	s_nop 0
	global_load_lds_dwordx4 v[206:207], off
	ds_read_b128 v[206:209], v161
	ds_read_b128 v[210:213], v161 offset:1024
	ds_read_b128 v[214:217], v161 offset:2048
	ds_read_b128 v[218:221], v161 offset:3072
	s_waitcnt vmcnt(8) lgkmcnt(0)
	s_barrier
	s_nop 0
	v_mfma_f32_16x16x32_bf16 v[124:127], v[152:155], v[174:177], v[124:127]
	v_mfma_f32_16x16x32_bf16 v[120:123], v[166:169], v[174:177], v[120:123]
	v_mfma_f32_16x16x32_bf16 v[116:119], v[152:155], v[182:185], v[116:119]
	v_mfma_f32_16x16x32_bf16 v[108:111], v[166:169], v[182:185], v[108:111]
	v_mfma_f32_16x16x32_bf16 v[100:103], v[152:155], v[190:193], v[100:103]
	v_mfma_f32_16x16x32_bf16 v[92:95], v[166:169], v[190:193], v[92:95]
	v_mfma_f32_16x16x32_bf16 v[84:87], v[152:155], v[198:201], v[84:87]
	v_mfma_f32_16x16x32_bf16 v[76:79], v[166:169], v[198:201], v[76:79]
	v_mfma_f32_16x16x32_bf16 v[124:127], v[162:165], v[178:181], v[124:127]
	v_mfma_f32_16x16x32_bf16 v[120:123], v[170:173], v[178:181], v[120:123]
	v_mfma_f32_16x16x32_bf16 v[116:119], v[162:165], v[186:189], v[116:119]
	v_mfma_f32_16x16x32_bf16 v[108:111], v[170:173], v[186:189], v[108:111]
	v_mfma_f32_16x16x32_bf16 v[100:103], v[162:165], v[194:197], v[100:103]
	v_mfma_f32_16x16x32_bf16 v[92:95], v[170:173], v[194:197], v[92:95]
	v_mfma_f32_16x16x32_bf16 v[84:87], v[162:165], v[202:205], v[84:87]
	v_mfma_f32_16x16x32_bf16 v[76:79], v[170:173], v[202:205], v[76:79]
	v_mfma_f32_16x16x32_bf16 v[112:115], v[206:209], v[174:177], v[112:115]
	v_mfma_f32_16x16x32_bf16 v[104:107], v[214:217], v[174:177], v[104:107]
	v_mfma_f32_16x16x32_bf16 v[96:99], v[206:209], v[182:185], v[96:99]
	v_mfma_f32_16x16x32_bf16 v[88:91], v[214:217], v[182:185], v[88:91]
	v_mfma_f32_16x16x32_bf16 v[80:83], v[206:209], v[190:193], v[80:83]
	v_mfma_f32_16x16x32_bf16 v[72:75], v[214:217], v[190:193], v[72:75]
	v_mfma_f32_16x16x32_bf16 v[68:71], v[206:209], v[198:201], v[68:71]
	v_mfma_f32_16x16x32_bf16 v[64:67], v[214:217], v[198:201], v[64:67]
	v_mfma_f32_16x16x32_bf16 v[112:115], v[210:213], v[178:181], v[112:115]
	v_mfma_f32_16x16x32_bf16 v[104:107], v[218:221], v[178:181], v[104:107]
	v_mfma_f32_16x16x32_bf16 v[96:99], v[210:213], v[186:189], v[96:99]
	v_mfma_f32_16x16x32_bf16 v[88:91], v[218:221], v[186:189], v[88:91]
	v_mfma_f32_16x16x32_bf16 v[80:83], v[210:213], v[194:197], v[80:83]
	v_mfma_f32_16x16x32_bf16 v[72:75], v[218:221], v[194:197], v[72:75]
	v_mfma_f32_16x16x32_bf16 v[68:71], v[210:213], v[202:205], v[68:71]
	v_mfma_f32_16x16x32_bf16 v[64:67], v[218:221], v[202:205], v[64:67]
	s_nop 0
	s_barrier
	s_add_i32 s79, s75, s33
	v_lshl_add_u64 v[222:223], s[62:63], 0, v[138:139]
	s_mov_b32 m0, s79
	global_load_lds_dwordx4 v[222:223], off
	v_lshl_add_u64 v[224:225], s[62:63], 0, v[142:143]
	s_add_i32 m0, s79, 0x2000
	s_nop 0
	global_load_lds_dwordx4 v[224:225], off
	s_mov_b32 m0, s35
	v_lshl_add_u64 v[226:227], s[64:65], 0, v[136:137]
	ds_read_b128 v[174:177], v160 offset:16384
	ds_read_b128 v[178:181], v160 offset:17408
	ds_read_b128 v[182:185], v160 offset:18432
	ds_read_b128 v[186:189], v160 offset:19456
	ds_read_b128 v[190:193], v160 offset:20480
	ds_read_b128 v[194:197], v160 offset:21504
	ds_read_b128 v[198:201], v160 offset:22528
	ds_read_b128 v[202:205], v160 offset:23552
	global_load_lds_dwordx4 v[226:227], off
	v_lshl_add_u64 v[228:229], s[64:65], 0, v[140:141]
	s_mov_b32 m0, s66
	s_nop 0
	global_load_lds_dwordx4 v[228:229], off
	s_add_u32 s80, s62, 0x40000
	s_addc_u32 s81, s63, 0
	s_add_i32 s79, s76, s33
	v_lshl_add_u64 v[240:241], s[80:81], 0, v[138:139]
	s_mov_b32 m0, s79
	s_nop 0
	global_load_lds_dwordx4 v[240:241], off
	v_lshl_add_u64 v[240:241], s[80:81], 0, v[142:143]
	s_add_i32 m0, s79, 0x2000
	s_nop 0
	global_load_lds_dwordx4 v[240:241], off
	s_waitcnt vmcnt(8) lgkmcnt(0)
	s_barrier
; #define PG8_STAGE(bufoff, gbase, voff) do { _Pragma("unroll") for (int _i = 0; _i < 2; ++_i) \
;         __builtin_amdgcn_global_load_lds((const unsigned*)((const char*)(gbase) + (voff)[_i]), (LAS unsigned*)(lds + (bufoff) + ldsw + _i * 8192), 16, 0, 0); } while (0)
; #define PG8_LDA(dst, b, h) do { _Pragma("unroll") for (int m = 0; m < 4; ++m) _Pragma("unroll") for (int k = 0; k < 2; ++k) dst[m][k] = *(const LAS bf16x8*)(lds + PG8_SA(b, h) + aoff + m * 2048 + k * 1024); } while (0)
; #define PG8_LDB(dst, b, h) do { _Pragma("unroll") for (int n = 0; n < 2; ++n) _Pragma("unroll") for (int k = 0; k < 2; ++k) dst[n][k] = *(const LAS bf16x8*)(lds + PG8_SB(b, h) + boff + n * 2048 + k * 1024); } while (0)
; #define PG8_MMA(ai, bj, At, Bt) do { __builtin_amdgcn_s_setprio(1); _Pragma("unroll") for (int m = 0; m < 4; ++m) _Pragma("unroll") for (int n = 0; n < 2; ++n) _Pragma("unroll") for (int k = 0; k < 2; ++k) \
;         acc[ai][bj][m][n] = __builtin_amdgcn_mfma_f32_16x16x32_bf16(Bt[n][k], At[m][k], acc[ai][bj][m][n], 0, 0, 0); __builtin_amdgcn_s_setprio(0); } while (0)
; #define PG8_WAIT_L(n) asm volatile("s_waitcnt lgkmcnt(" #n ")" ::: "memory")
; #define PG8_BAR __builtin_amdgcn_s_barrier()
; #define PG8_SCHED __builtin_amdgcn_sched_barrier(0)
; template <class Epi>
; __device__ __forceinline__ void gemm_phase(LAS unsigned char* lds, const Gemm g, const StaticOrder& S, const Epi& E) {
;     ...
;             PG8_LDB(B0, 1, 0); PG8_SCHED; PG8_LDA(At, 1, 0); PG8_STAGE(PG8_SA(0, 1), a2 + hstepA, voffA);
;             PG8_WAIT_L(8); PG8_BAR; PG8_WAIT_L(0); PG8_MMA(0, 0, At, B0); PG8_BAR; PG8_SCHED;
;             PG8_LDB(B1, 1, 1); PG8_STAGE(PG8_SB(1, 0), b3, voffB);
;             PG8_BAR; PG8_WAIT_L(0); PG8_MMA(0, 1, At, B1); PG8_BAR;
;             PG8_LDA(At, 1, 1); PG8_STAGE(PG8_SA(1, 0), a3, voffA);
;             PG8_BAR; PG8_WAIT_L(0); PG8_MMA(1, 0, At, B0); PG8_BAR; PG8_SCHED;
	s_nop 0
	v_mfma_f32_16x16x32_bf16 v[60:63], v[152:155], v[174:177], v[60:63]
	v_mfma_f32_16x16x32_bf16 v[56:59], v[166:169], v[174:177], v[56:59]
	v_mfma_f32_16x16x32_bf16 v[52:55], v[152:155], v[182:185], v[52:55]
	v_mfma_f32_16x16x32_bf16 v[44:47], v[166:169], v[182:185], v[44:47]
	v_mfma_f32_16x16x32_bf16 v[36:39], v[152:155], v[190:193], v[36:39]
	v_mfma_f32_16x16x32_bf16 v[28:31], v[166:169], v[190:193], v[28:31]
	v_mfma_f32_16x16x32_bf16 v[20:23], v[152:155], v[198:201], v[20:23]
	v_mfma_f32_16x16x32_bf16 v[12:15], v[166:169], v[198:201], v[12:15]
	v_mfma_f32_16x16x32_bf16 v[60:63], v[162:165], v[178:181], v[60:63]
	v_mfma_f32_16x16x32_bf16 v[56:59], v[170:173], v[178:181], v[56:59]
	v_mfma_f32_16x16x32_bf16 v[52:55], v[162:165], v[186:189], v[52:55]
	v_mfma_f32_16x16x32_bf16 v[44:47], v[170:173], v[186:189], v[44:47]
	v_mfma_f32_16x16x32_bf16 v[36:39], v[162:165], v[194:197], v[36:39]
	v_mfma_f32_16x16x32_bf16 v[28:31], v[170:173], v[194:197], v[28:31]
	v_mfma_f32_16x16x32_bf16 v[20:23], v[162:165], v[202:205], v[20:23]
	v_mfma_f32_16x16x32_bf16 v[12:15], v[170:173], v[202:205], v[12:15]
	v_mfma_f32_16x16x32_bf16 v[48:51], v[206:209], v[174:177], v[48:51]
	v_mfma_f32_16x16x32_bf16 v[40:43], v[214:217], v[174:177], v[40:43]
	v_mfma_f32_16x16x32_bf16 v[32:35], v[206:209], v[182:185], v[32:35]
	v_mfma_f32_16x16x32_bf16 v[24:27], v[214:217], v[182:185], v[24:27]
	v_mfma_f32_16x16x32_bf16 v[16:19], v[206:209], v[190:193], v[16:19]
	v_mfma_f32_16x16x32_bf16 v[8:11], v[214:217], v[190:193], v[8:11]
	v_mfma_f32_16x16x32_bf16 v[4:7], v[206:209], v[198:201], v[4:7]
	v_mfma_f32_16x16x32_bf16 v[0:3], v[214:217], v[198:201], v[0:3]
	v_mfma_f32_16x16x32_bf16 v[48:51], v[210:213], v[178:181], v[48:51]
	v_mfma_f32_16x16x32_bf16 v[40:43], v[218:221], v[178:181], v[40:43]
	v_mfma_f32_16x16x32_bf16 v[32:35], v[210:213], v[186:189], v[32:35]
	v_mfma_f32_16x16x32_bf16 v[24:27], v[218:221], v[186:189], v[24:27]
	v_mfma_f32_16x16x32_bf16 v[16:19], v[210:213], v[194:197], v[16:19]
	v_mfma_f32_16x16x32_bf16 v[8:11], v[218:221], v[194:197], v[8:11]
	v_mfma_f32_16x16x32_bf16 v[4:7], v[210:213], v[202:205], v[4:7]
	v_mfma_f32_16x16x32_bf16 v[0:3], v[218:221], v[202:205], v[0:3]
	s_nop 0
	s_barrier
	s_add_i32 s79, 0, 0x18000
	v_add_u32_e32 v170, s79, v156
	ds_read_b128 v[152:155], v170
	ds_read_b128 v[162:165], v170 offset:1024
	ds_read_b128 v[166:169], v170 offset:2048
	ds_read_b128 v[170:173], v170 offset:3072
	s_add_u32 s64, s64, 0x40000
	s_addc_u32 s65, s65, 0
	s_mov_b32 m0, s67
	v_lshl_add_u64 v[206:207], s[64:65], 0, v[136:137]
	ds_read_b128 v[174:177], v160 offset:32768
	ds_read_b128 v[178:181], v160 offset:33792
	ds_read_b128 v[182:185], v160 offset:34816
	ds_read_b128 v[186:189], v160 offset:35840
	ds_read_b128 v[190:193], v160 offset:36864
	ds_read_b128 v[194:197], v160 offset:37888
	ds_read_b128 v[198:201], v160 offset:38912
	ds_read_b128 v[202:205], v160 offset:39936
	global_load_lds_dwordx4 v[206:207], off
	v_lshl_add_u64 v[206:207], s[64:65], 0, v[140:141]
	s_mov_b32 m0, s68
	s_nop 0
	global_load_lds_dwordx4 v[206:207], off
	s_add_i32 s64, 0, 0x1c000
	v_add_u32_e32 v218, s64, v156
	ds_read_b128 v[206:209], v218
	ds_read_b128 v[210:213], v218 offset:1024
	ds_read_b128 v[214:217], v218 offset:2048
	ds_read_b128 v[218:221], v218 offset:3072
	s_waitcnt vmcnt(8) lgkmcnt(0)
	s_barrier
	s_nop 0
	v_mfma_f32_16x16x32_bf16 v[124:127], v[152:155], v[174:177], v[124:127]
	v_mfma_f32_16x16x32_bf16 v[120:123], v[166:169], v[174:177], v[120:123]
	v_mfma_f32_16x16x32_bf16 v[116:119], v[152:155], v[182:185], v[116:119]
	v_mfma_f32_16x16x32_bf16 v[108:111], v[166:169], v[182:185], v[108:111]
	v_mfma_f32_16x16x32_bf16 v[100:103], v[152:155], v[190:193], v[100:103]
	v_mfma_f32_16x16x32_bf16 v[92:95], v[166:169], v[190:193], v[92:95]
	v_mfma_f32_16x16x32_bf16 v[84:87], v[152:155], v[198:201], v[84:87]
	v_mfma_f32_16x16x32_bf16 v[76:79], v[166:169], v[198:201], v[76:79]
	v_mfma_f32_16x16x32_bf16 v[124:127], v[162:165], v[178:181], v[124:127]
	v_mfma_f32_16x16x32_bf16 v[120:123], v[170:173], v[178:181], v[120:123]
	v_mfma_f32_16x16x32_bf16 v[116:119], v[162:165], v[186:189], v[116:119]
	v_mfma_f32_16x16x32_bf16 v[108:111], v[170:173], v[186:189], v[108:111]
	v_mfma_f32_16x16x32_bf16 v[100:103], v[162:165], v[194:197], v[100:103]
	v_mfma_f32_16x16x32_bf16 v[92:95], v[170:173], v[194:197], v[92:95]
	v_mfma_f32_16x16x32_bf16 v[84:87], v[162:165], v[202:205], v[84:87]
	v_mfma_f32_16x16x32_bf16 v[76:79], v[170:173], v[202:205], v[76:79]
	v_mfma_f32_16x16x32_bf16 v[112:115], v[206:209], v[174:177], v[112:115]
	v_mfma_f32_16x16x32_bf16 v[104:107], v[214:217], v[174:177], v[104:107]
	v_mfma_f32_16x16x32_bf16 v[96:99], v[206:209], v[182:185], v[96:99]
	v_mfma_f32_16x16x32_bf16 v[88:91], v[214:217], v[182:185], v[88:91]
	v_mfma_f32_16x16x32_bf16 v[80:83], v[206:209], v[190:193], v[80:83]
	v_mfma_f32_16x16x32_bf16 v[72:75], v[214:217], v[190:193], v[72:75]
	v_mfma_f32_16x16x32_bf16 v[68:71], v[206:209], v[198:201], v[68:71]
	v_mfma_f32_16x16x32_bf16 v[64:67], v[214:217], v[198:201], v[64:67]
	v_mfma_f32_16x16x32_bf16 v[112:115], v[210:213], v[178:181], v[112:115]
	v_mfma_f32_16x16x32_bf16 v[104:107], v[218:221], v[178:181], v[104:107]
	v_mfma_f32_16x16x32_bf16 v[96:99], v[210:213], v[186:189], v[96:99]
	v_mfma_f32_16x16x32_bf16 v[88:91], v[218:221], v[186:189], v[88:91]
	v_mfma_f32_16x16x32_bf16 v[80:83], v[210:213], v[194:197], v[80:83]
	v_mfma_f32_16x16x32_bf16 v[72:75], v[218:221], v[194:197], v[72:75]
	v_mfma_f32_16x16x32_bf16 v[68:71], v[210:213], v[202:205], v[68:71]
	v_mfma_f32_16x16x32_bf16 v[64:67], v[218:221], v[202:205], v[64:67]
	s_nop 0
	s_barrier
; __device__ __forceinline__ unsigned pk2(float lo, float hi) { unsigned r; asm("v_cvt_pk_bf16_f32 %0, %1, %2" : "=v"(r) : "v"(lo), "v"(hi)); return r; }
; __device__ __forceinline__ float gelu_t(float x) { return x * __builtin_amdgcn_rcpf(1.f + __expf(-1.5957691216057308f * (x + 0.044715f * x * x * x))); }
; #define PG8_STAGE(bufoff, gbase, voff) do { _Pragma("unroll") for (int _i = 0; _i < 2; ++_i) \
;         __builtin_amdgcn_global_load_lds((const unsigned*)((const char*)(gbase) + (voff)[_i]), (LAS unsigned*)(lds + (bufoff) + ldsw + _i * 8192), 16, 0, 0); } while (0)
; #define PG8_MMA(ai, bj, At, Bt) do { __builtin_amdgcn_s_setprio(1); _Pragma("unroll") for (int m = 0; m < 4; ++m) _Pragma("unroll") for (int n = 0; n < 2; ++n) _Pragma("unroll") for (int k = 0; k < 2; ++k) \
;         acc[ai][bj][m][n] = __builtin_amdgcn_mfma_f32_16x16x32_bf16(Bt[n][k], At[m][k], acc[ai][bj][m][n], 0, 0, 0); __builtin_amdgcn_s_setprio(0); } while (0)
; #define PG8_WAIT_V(n) asm volatile("s_waitcnt vmcnt(" #n ")" ::: "memory")
; #define PG8_BAR __builtin_amdgcn_s_barrier()
;     __device__ __forceinline__ void operator()(const f32x4 (&acc)[2][2][4][2], const Unit& u, int wr, int wc, int fr, int fq) const {
;     ...
;             for (int m = 0; m < 4; ++m) { const int row = row0 + ai * HALF + m * 16; u16* rowp = O + (size_t)row * ldc + col0;
; #pragma unroll
;                 for (int bj = 0; bj < 2; ++bj) { f32x4 v0 = acc[ai][bj][m][0], v1 = acc[ai][bj][m][1];
;                     if (col0 + bj * HALF >= gelu_from) { v0 = (f32x4){gelu_t(v0.x), gelu_t(v0.y), gelu_t(v0.z), gelu_t(v0.w)}; v1 = (f32x4){gelu_t(v1.x), gelu_t(v1.y), gelu_t(v1.z), gelu_t(v1.w)}; }
;                     u32x4 w; w.x = pk2(v0[0], v0[1]); w.y = pk2(v0[2], v0[3]); w.z = pk2(v1[0], v1[1]); w.w = pk2(v1[2], v1[3]);
;                     *(u32x4*)(rowp + bj * HALF) = w;
;                     if (halo != nullptr && m == 3 && fr >= 14) *(u32x4*)(halo + (size_t)((row >> 6) * 2 + (fr - 14)) * ldc + col0 + bj * HALF) = w; } }
; template <class Epi>
; __device__ __forceinline__ void gemm_phase(LAS unsigned char* lds, const Gemm g, const StaticOrder& S, const Epi& E) {
;     ...
;             PG8_STAGE(PG8_SB(1, 1), b3 + hstepB, voffB);
;             PG8_WAIT_V(6); PG8_BAR; PG8_MMA(1, 1, At, B1); PG8_BAR;
	s_add_i32 s65, s79, s33
	v_lshl_add_u64 v[222:223], v[222:223], 0, s[28:29]
	s_mov_b32 m0, s65
	global_load_lds_dwordx4 v[222:223], off
	v_lshl_add_u64 v[222:223], v[224:225], 0, s[28:29]
	s_add_i32 m0, s65, 0x2000
	s_nop 0
	global_load_lds_dwordx4 v[222:223], off
	s_mov_b32 m0, s71
	v_lshl_add_u64 v[222:223], v[226:227], 0, s[28:29]
	ds_read_b128 v[174:177], v160 offset:49152
	ds_read_b128 v[178:181], v160 offset:50176
	ds_read_b128 v[182:185], v160 offset:51200
	ds_read_b128 v[186:189], v160 offset:52224
	ds_read_b128 v[190:193], v160 offset:53248
	ds_read_b128 v[194:197], v160 offset:54272
	ds_read_b128 v[198:201], v160 offset:55296
	ds_read_b128 v[202:205], v160 offset:56320
	global_load_lds_dwordx4 v[222:223], off
	v_lshl_add_u64 v[222:223], v[228:229], 0, s[28:29]
	s_mov_b32 m0, s72
	s_nop 0
	global_load_lds_dwordx4 v[222:223], off
	s_add_u32 s62, s62, 0x40080
	s_addc_u32 s63, s63, 0
	s_add_i32 s64, s64, s33
	v_lshl_add_u64 v[240:241], s[62:63], 0, v[138:139]
	s_mov_b32 m0, s64
	s_nop 0
	global_load_lds_dwordx4 v[240:241], off
	v_lshl_add_u64 v[240:241], s[62:63], 0, v[142:143]
	s_add_i32 m0, s64, 0x2000
	s_nop 0
	global_load_lds_dwordx4 v[240:241], off
	s_waitcnt vmcnt(8) lgkmcnt(0)
	s_barrier
	s_nop 0
	v_mfma_f32_16x16x32_bf16 v[60:63], v[152:155], v[174:177], v[60:63]
	v_mfma_f32_16x16x32_bf16 v[56:59], v[166:169], v[174:177], v[56:59]
	v_mfma_f32_16x16x32_bf16 v[52:55], v[152:155], v[182:185], v[52:55]
	v_mfma_f32_16x16x32_bf16 v[44:47], v[166:169], v[182:185], v[44:47]
	v_mfma_f32_16x16x32_bf16 v[36:39], v[152:155], v[190:193], v[36:39]
	v_mfma_f32_16x16x32_bf16 v[28:31], v[166:169], v[190:193], v[28:31]
	v_mfma_f32_16x16x32_bf16 v[20:23], v[152:155], v[198:201], v[20:23]
	v_mfma_f32_16x16x32_bf16 v[12:15], v[166:169], v[198:201], v[12:15]
	v_mfma_f32_16x16x32_bf16 v[60:63], v[162:165], v[178:181], v[60:63]
	v_mfma_f32_16x16x32_bf16 v[56:59], v[170:173], v[178:181], v[56:59]
	v_mfma_f32_16x16x32_bf16 v[52:55], v[162:165], v[186:189], v[52:55]
	v_mfma_f32_16x16x32_bf16 v[44:47], v[170:173], v[186:189], v[44:47]
	v_mfma_f32_16x16x32_bf16 v[36:39], v[162:165], v[194:197], v[36:39]
	v_mfma_f32_16x16x32_bf16 v[28:31], v[170:173], v[194:197], v[28:31]
	v_mfma_f32_16x16x32_bf16 v[20:23], v[162:165], v[202:205], v[20:23]
	v_mfma_f32_16x16x32_bf16 v[12:15], v[170:173], v[202:205], v[12:15]
	v_mfma_f32_16x16x32_bf16 v[48:51], v[206:209], v[174:177], v[48:51]
	v_mfma_f32_16x16x32_bf16 v[40:43], v[214:217], v[174:177], v[40:43]
	v_mfma_f32_16x16x32_bf16 v[32:35], v[206:209], v[182:185], v[32:35]
	v_mfma_f32_16x16x32_bf16 v[24:27], v[214:217], v[182:185], v[24:27]
	v_mfma_f32_16x16x32_bf16 v[16:19], v[206:209], v[190:193], v[16:19]
	v_mfma_f32_16x16x32_bf16 v[8:11], v[214:217], v[190:193], v[8:11]
	v_mfma_f32_16x16x32_bf16 v[4:7], v[206:209], v[198:201], v[4:7]
	v_mfma_f32_16x16x32_bf16 v[0:3], v[214:217], v[198:201], v[0:3]
	v_mfma_f32_16x16x32_bf16 v[48:51], v[210:213], v[178:181], v[48:51]
	v_mfma_f32_16x16x32_bf16 v[40:43], v[218:221], v[178:181], v[40:43]
	v_mfma_f32_16x16x32_bf16 v[32:35], v[210:213], v[186:189], v[32:35]
	v_mfma_f32_16x16x32_bf16 v[24:27], v[218:221], v[186:189], v[24:27]
	v_mfma_f32_16x16x32_bf16 v[16:19], v[210:213], v[194:197], v[16:19]
	v_mfma_f32_16x16x32_bf16 v[8:11], v[218:221], v[194:197], v[8:11]
	v_mfma_f32_16x16x32_bf16 v[4:7], v[210:213], v[202:205], v[4:7]
	v_mfma_f32_16x16x32_bf16 v[0:3], v[218:221], v[202:205], v[0:3]
	s_nop 0
	s_add_i32 s78, s78, 2
	s_add_u32 s60, s60, 0x100
	s_addc_u32 s61, s61, 0
	s_add_u32 s37, s37, 0x100
	s_addc_u32 s39, s39, 0
	s_cmp_gt_u32 s78, 13
	s_barrier
	s_cbranch_scc0 .LBB0_682
	s_lshl_b32 s37, s58, 8
	s_add_i32 s37, s37, s70
	v_lshl_or_b32 v152, s59, 8, v158
	v_or_b32_e32 v162, s37, v135
	v_ashrrev_i32_e32 v153, 31, v152
	v_mov_b64_e32 v[164:165], s[4:5]
	v_mad_i64_i32 v[166:167], s[58:59], v162, s77, v[164:165]
	v_lshlrev_b64 v[154:155], 1, v[152:153]
	v_cvt_pk_bf16_f32 v112, v112, v113
	v_cvt_pk_bf16_f32 v113, v114, v115
	v_cvt_pk_bf16_f32 v114, v104, v105
	v_or_b32_e32 v104, 16, v162
	v_lshl_add_u64 v[166:167], v[166:167], 0, v[154:155]
	v_mad_i64_i32 v[104:105], s[58:59], v104, s77, v[164:165]
	v_cvt_pk_bf16_f32 v96, v96, v97
	v_cvt_pk_bf16_f32 v97, v98, v99
	v_cvt_pk_bf16_f32 v98, v88, v89
	v_or_b32_e32 v88, 32, v162
	v_cvt_pk_bf16_f32 v115, v106, v107
	global_store_dwordx4 v[166:167], v[112:115], off offset:256
	v_mad_i64_i32 v[88:89], s[58:59], v88, s77, v[164:165]
	s_nop 0
	v_lshl_add_u64 v[112:113], v[104:105], 0, v[154:155]
	v_cvt_pk_bf16_f32 v80, v80, v81
	v_cvt_pk_bf16_f32 v81, v82, v83
	v_cvt_pk_bf16_f32 v82, v72, v73
	v_or_b32_e32 v72, 48, v162
	s_ashr_i32 s37, s37, 5
	v_cvt_pk_bf16_f32 v99, v90, v91
	global_store_dwordx4 v[112:113], v[96:99], off offset:256
	v_mad_i64_i32 v[72:73], s[58:59], v72, s77, v[164:165]
	s_nop 0
	v_lshl_add_u64 v[96:97], v[88:89], 0, v[154:155]
	v_add_u32_e32 v163, s37, v157
	v_cvt_pk_bf16_f32 v83, v74, v75
	global_store_dwordx4 v[96:97], v[80:83], off offset:256
	v_cvt_pk_bf16_f32 v124, v124, v125
	v_cvt_pk_bf16_f32 v125, v126, v127
	v_cvt_pk_bf16_f32 v126, v120, v121
	v_cvt_pk_bf16_f32 v127, v122, v123
	global_store_dwordx4 v[166:167], v[124:127], off
	s_nop 0
	v_lshl_add_u64 v[80:81], v[72:73], 0, v[154:155]
	v_cvt_pk_bf16_f32 v104, v116, v117
	v_cvt_pk_bf16_f32 v105, v118, v119
	v_cvt_pk_bf16_f32 v106, v108, v109
	v_cvt_pk_bf16_f32 v107, v110, v111
	global_store_dwordx4 v[112:113], v[104:107], off
	v_cvt_pk_bf16_f32 v88, v100, v101
	v_cvt_pk_bf16_f32 v89, v102, v103
	v_cvt_pk_bf16_f32 v90, v92, v93
	v_cvt_pk_bf16_f32 v91, v94, v95
	global_store_dwordx4 v[96:97], v[88:91], off
	v_cvt_pk_bf16_f32 v72, v84, v85
	v_cvt_pk_bf16_f32 v73, v86, v87
	v_cvt_pk_bf16_f32 v74, v76, v77
	v_cvt_pk_bf16_f32 v75, v78, v79
	global_store_dwordx4 v[80:81], v[72:75], off
	s_and_saveexec_b64 s[58:59], s[0:1]
	s_cbranch_execz .LBB0_685
	v_mov_b64_e32 v[76:77], s[18:19]
	v_mad_i64_i32 v[76:77], s[60:61], v163, s77, v[76:77]
	v_lshl_add_u64 v[76:77], v[152:153], 1, v[76:77]
	global_store_dwordx4 v[76:77], v[72:75], off

; #define PG8_STAGE(bufoff, gbase, voff) do { _Pragma("unroll") for (int _i = 0; _i < 2; ++_i) \
;         __builtin_amdgcn_global_load_lds((const unsigned*)((const char*)(gbase) + (voff)[_i]), (LAS unsigned*)(lds + (bufoff) + ldsw + _i * 8192), 16, 0, 0); } while (0)
; #define PG8_LDA(dst, b, h) do { _Pragma("unroll") for (int m = 0; m < 4; ++m) _Pragma("unroll") for (int k = 0; k < 2; ++k) dst[m][k] = *(const LAS bf16x8*)(lds + PG8_SA(b, h) + aoff + m * 2048 + k * 1024); } while (0)
; #define PG8_LDB(dst, b, h) do { _Pragma("unroll") for (int n = 0; n < 2; ++n) _Pragma("unroll") for (int k = 0; k < 2; ++k) dst[n][k] = *(const LAS bf16x8*)(lds + PG8_SB(b, h) + boff + n * 2048 + k * 1024); } while (0)
; #define PG8_MMA(ai, bj, At, Bt) do { __builtin_amdgcn_s_setprio(1); _Pragma("unroll") for (int m = 0; m < 4; ++m) _Pragma("unroll") for (int n = 0; n < 2; ++n) _Pragma("unroll") for (int k = 0; k < 2; ++k) \
;         acc[ai][bj][m][n] = __builtin_amdgcn_mfma_f32_16x16x32_bf16(Bt[n][k], At[m][k], acc[ai][bj][m][n], 0, 0, 0); __builtin_amdgcn_s_setprio(0); } while (0)
; #define PG8_WAIT_V(n) asm volatile("s_waitcnt vmcnt(" #n ")" ::: "memory")
; #define PG8_WAIT_L(n) asm volatile("s_waitcnt lgkmcnt(" #n ")" ::: "memory")
; #define PG8_BAR __builtin_amdgcn_s_barrier()
; #define PG8_SCHED __builtin_amdgcn_sched_barrier(0)
; template <class Epi>
; __device__ __forceinline__ void gemm_phase(LAS unsigned char* lds, const Gemm g, const StaticOrder& S, const Epi& E) {
;     ...
;             PG8_LDB(B0, 0, 0); PG8_SCHED; PG8_LDA(At, 0, 0); PG8_STAGE(PG8_SA(1, 1), a1 + hstepA, voffA);
;             PG8_WAIT_L(8); PG8_BAR; PG8_WAIT_L(0); PG8_MMA(0, 0, At, B0); PG8_BAR; PG8_SCHED;
;             PG8_LDB(B1, 0, 1); PG8_STAGE(PG8_SB(0, 0), b2, voffB);
;             PG8_BAR; PG8_WAIT_L(0); PG8_MMA(0, 1, At, B1); PG8_BAR;
;             PG8_LDA(At, 0, 1); PG8_STAGE(PG8_SA(0, 0), a2, voffA);
;             PG8_BAR; PG8_WAIT_L(0); PG8_MMA(1, 0, At, B0); PG8_BAR; PG8_SCHED;
;             PG8_STAGE(PG8_SB(0, 1), b2 + hstepB, voffB);
;             PG8_WAIT_V(6); PG8_BAR; PG8_MMA(1, 1, At, B1); PG8_BAR;
.LBB0_910:
	ds_read_b128 v[150:153], v170
	ds_read_b128 v[154:157], v170 offset:1024
	ds_read_b128 v[174:177], v170 offset:2048
	ds_read_b128 v[178:181], v170 offset:3072
	s_add_i32 s83, s54, 2
	s_add_u32 s55, s46, 0xffea0080
	s_addc_u32 s56, s47, -1
	s_cmp_eq_u32 s18, s54
	s_cselect_b32 s54, s0, s41
	s_cselect_b32 s57, s45, s56
	s_cselect_b32 s56, s44, s55
	s_cselect_b32 s55, s1, s82
	v_lshl_add_u64 v[158:159], s[46:47], 0, v[144:145]
	s_add_i32 m0, s33, 0xc000
	ds_read_b128 v[182:185], v171
	ds_read_b128 v[186:189], v171 offset:1024
	ds_read_b128 v[190:193], v171 offset:2048
	ds_read_b128 v[194:197], v171 offset:3072
	ds_read_b128 v[198:201], v171 offset:4096
	ds_read_b128 v[202:205], v171 offset:5120
	ds_read_b128 v[206:209], v171 offset:6144
	ds_read_b128 v[210:213], v171 offset:7168
	global_load_lds_dwordx4 v[158:159], off
	v_lshl_add_u64 v[158:159], s[46:47], 0, v[146:147]
	s_add_i32 m0, s33, 0xe000
	s_nop 0
	global_load_lds_dwordx4 v[158:159], off
	ds_read_b128 v[214:217], v172
	ds_read_b128 v[218:221], v172 offset:1024
	ds_read_b128 v[222:225], v172 offset:2048
	ds_read_b128 v[226:229], v172 offset:3072
	s_waitcnt vmcnt(8) lgkmcnt(0)
	s_barrier
	s_nop 0
	v_mfma_f32_16x16x32_bf16 v[124:127], v[150:153], v[182:185], v[124:127]
	v_mfma_f32_16x16x32_bf16 v[120:123], v[174:177], v[182:185], v[120:123]
	v_mfma_f32_16x16x32_bf16 v[116:119], v[150:153], v[190:193], v[116:119]
	v_mfma_f32_16x16x32_bf16 v[108:111], v[174:177], v[190:193], v[108:111]
	v_mfma_f32_16x16x32_bf16 v[100:103], v[150:153], v[198:201], v[100:103]
	v_mfma_f32_16x16x32_bf16 v[92:95], v[174:177], v[198:201], v[92:95]
	v_mfma_f32_16x16x32_bf16 v[84:87], v[150:153], v[206:209], v[84:87]
	v_mfma_f32_16x16x32_bf16 v[76:79], v[174:177], v[206:209], v[76:79]
	v_mfma_f32_16x16x32_bf16 v[124:127], v[154:157], v[186:189], v[124:127]
	v_mfma_f32_16x16x32_bf16 v[120:123], v[178:181], v[186:189], v[120:123]
	v_mfma_f32_16x16x32_bf16 v[116:119], v[154:157], v[194:197], v[116:119]
	v_mfma_f32_16x16x32_bf16 v[108:111], v[178:181], v[194:197], v[108:111]
	v_mfma_f32_16x16x32_bf16 v[100:103], v[154:157], v[202:205], v[100:103]
	v_mfma_f32_16x16x32_bf16 v[92:95], v[178:181], v[202:205], v[92:95]
	v_mfma_f32_16x16x32_bf16 v[84:87], v[154:157], v[210:213], v[84:87]
	v_mfma_f32_16x16x32_bf16 v[76:79], v[178:181], v[210:213], v[76:79]
	v_mfma_f32_16x16x32_bf16 v[112:115], v[214:217], v[182:185], v[112:115]
	v_mfma_f32_16x16x32_bf16 v[104:107], v[222:225], v[182:185], v[104:107]
	v_mfma_f32_16x16x32_bf16 v[96:99], v[214:217], v[190:193], v[96:99]
	v_mfma_f32_16x16x32_bf16 v[88:91], v[222:225], v[190:193], v[88:91]
	v_mfma_f32_16x16x32_bf16 v[80:83], v[214:217], v[198:201], v[80:83]
	v_mfma_f32_16x16x32_bf16 v[72:75], v[222:225], v[198:201], v[72:75]
	v_mfma_f32_16x16x32_bf16 v[68:71], v[214:217], v[206:209], v[68:71]
	v_mfma_f32_16x16x32_bf16 v[64:67], v[222:225], v[206:209], v[64:67]
	v_mfma_f32_16x16x32_bf16 v[112:115], v[218:221], v[186:189], v[112:115]
	v_mfma_f32_16x16x32_bf16 v[104:107], v[226:229], v[186:189], v[104:107]
	v_mfma_f32_16x16x32_bf16 v[96:99], v[218:221], v[194:197], v[96:99]
	v_mfma_f32_16x16x32_bf16 v[88:91], v[226:229], v[194:197], v[88:91]
	v_mfma_f32_16x16x32_bf16 v[80:83], v[218:221], v[202:205], v[80:83]
	v_mfma_f32_16x16x32_bf16 v[72:75], v[226:229], v[202:205], v[72:75]
	v_mfma_f32_16x16x32_bf16 v[68:71], v[218:221], v[210:213], v[68:71]
	v_mfma_f32_16x16x32_bf16 v[64:67], v[226:229], v[210:213], v[64:67]
	s_nop 0
	s_barrier
	s_add_i32 s84, s65, s21
	v_lshl_add_u64 v[158:159], s[54:55], 0, v[138:139]
	s_mov_b32 m0, s84
	global_load_lds_dwordx4 v[158:159], off
	v_lshl_add_u64 v[230:231], s[54:55], 0, v[142:143]
	s_add_i32 m0, s84, 0x2000
	s_nop 0
	global_load_lds_dwordx4 v[230:231], off
	s_mov_b32 m0, s33
	v_lshl_add_u64 v[232:233], s[56:57], 0, v[136:137]
	ds_read_b128 v[182:185], v171 offset:16384
	ds_read_b128 v[186:189], v171 offset:17408
	ds_read_b128 v[190:193], v171 offset:18432
	ds_read_b128 v[194:197], v171 offset:19456
	ds_read_b128 v[198:201], v171 offset:20480
	ds_read_b128 v[202:205], v171 offset:21504
	ds_read_b128 v[206:209], v171 offset:22528
	ds_read_b128 v[210:213], v171 offset:23552
	global_load_lds_dwordx4 v[232:233], off
	v_lshl_add_u64 v[234:235], s[56:57], 0, v[140:141]
	s_mov_b32 m0, s35
	s_nop 0
	global_load_lds_dwordx4 v[234:235], off
	s_add_u32 s84, s54, 0xb0000
	s_addc_u32 s85, s55, 0
	s_add_i32 s86, s66, s21
	v_lshl_add_u64 v[240:241], s[84:85], 0, v[138:139]
	s_mov_b32 m0, s86
	s_nop 0
	global_load_lds_dwordx4 v[240:241], off
	v_lshl_add_u64 v[240:241], s[84:85], 0, v[142:143]
	s_add_i32 m0, s86, 0x2000
	s_nop 0
	global_load_lds_dwordx4 v[240:241], off
	s_waitcnt vmcnt(8) lgkmcnt(0)
	s_barrier
; #define PG8_STAGE(bufoff, gbase, voff) do { _Pragma("unroll") for (int _i = 0; _i < 2; ++_i) \
;         __builtin_amdgcn_global_load_lds((const unsigned*)((const char*)(gbase) + (voff)[_i]), (LAS unsigned*)(lds + (bufoff) + ldsw + _i * 8192), 16, 0, 0); } while (0)
; #define PG8_LDA(dst, b, h) do { _Pragma("unroll") for (int m = 0; m < 4; ++m) _Pragma("unroll") for (int k = 0; k < 2; ++k) dst[m][k] = *(const LAS bf16x8*)(lds + PG8_SA(b, h) + aoff + m * 2048 + k * 1024); } while (0)
; #define PG8_LDB(dst, b, h) do { _Pragma("unroll") for (int n = 0; n < 2; ++n) _Pragma("unroll") for (int k = 0; k < 2; ++k) dst[n][k] = *(const LAS bf16x8*)(lds + PG8_SB(b, h) + boff + n * 2048 + k * 1024); } while (0)
; #define PG8_MMA(ai, bj, At, Bt) do { __builtin_amdgcn_s_setprio(1); _Pragma("unroll") for (int m = 0; m < 4; ++m) _Pragma("unroll") for (int n = 0; n < 2; ++n) _Pragma("unroll") for (int k = 0; k < 2; ++k) \
;         acc[ai][bj][m][n] = __builtin_amdgcn_mfma_f32_16x16x32_bf16(Bt[n][k], At[m][k], acc[ai][bj][m][n], 0, 0, 0); __builtin_amdgcn_s_setprio(0); } while (0)
; #define PG8_WAIT_L(n) asm volatile("s_waitcnt lgkmcnt(" #n ")" ::: "memory")
; #define PG8_BAR __builtin_amdgcn_s_barrier()
; #define PG8_SCHED __builtin_amdgcn_sched_barrier(0)
; template <class Epi>
; __device__ __forceinline__ void gemm_phase(LAS unsigned char* lds, const Gemm g, const StaticOrder& S, const Epi& E) {
;     ...
;             PG8_LDB(B0, 1, 0); PG8_SCHED; PG8_LDA(At, 1, 0); PG8_STAGE(PG8_SA(0, 1), a2 + hstepA, voffA);
;             PG8_WAIT_L(8); PG8_BAR; PG8_WAIT_L(0); PG8_MMA(0, 0, At, B0); PG8_BAR; PG8_SCHED;
;             PG8_LDB(B1, 1, 1); PG8_STAGE(PG8_SB(1, 0), b3, voffB);
;             PG8_BAR; PG8_WAIT_L(0); PG8_MMA(0, 1, At, B1); PG8_BAR;
;             PG8_LDA(At, 1, 1); PG8_STAGE(PG8_SA(1, 0), a3, voffA);
;             PG8_BAR; PG8_WAIT_L(0); PG8_MMA(1, 0, At, B0); PG8_BAR; PG8_SCHED;
	s_nop 0
	v_mfma_f32_16x16x32_bf16 v[60:63], v[150:153], v[182:185], v[60:63]
	v_mfma_f32_16x16x32_bf16 v[56:59], v[174:177], v[182:185], v[56:59]
	v_mfma_f32_16x16x32_bf16 v[52:55], v[150:153], v[190:193], v[52:55]
	v_mfma_f32_16x16x32_bf16 v[44:47], v[174:177], v[190:193], v[44:47]
	v_mfma_f32_16x16x32_bf16 v[36:39], v[150:153], v[198:201], v[36:39]
	v_mfma_f32_16x16x32_bf16 v[28:31], v[174:177], v[198:201], v[28:31]
	v_mfma_f32_16x16x32_bf16 v[20:23], v[150:153], v[206:209], v[20:23]
	v_mfma_f32_16x16x32_bf16 v[12:15], v[174:177], v[206:209], v[12:15]
	v_mfma_f32_16x16x32_bf16 v[60:63], v[154:157], v[186:189], v[60:63]
	v_mfma_f32_16x16x32_bf16 v[56:59], v[178:181], v[186:189], v[56:59]
	v_mfma_f32_16x16x32_bf16 v[52:55], v[154:157], v[194:197], v[52:55]
	v_mfma_f32_16x16x32_bf16 v[44:47], v[178:181], v[194:197], v[44:47]
	v_mfma_f32_16x16x32_bf16 v[36:39], v[154:157], v[202:205], v[36:39]
	v_mfma_f32_16x16x32_bf16 v[28:31], v[178:181], v[202:205], v[28:31]
	v_mfma_f32_16x16x32_bf16 v[20:23], v[154:157], v[210:213], v[20:23]
	v_mfma_f32_16x16x32_bf16 v[12:15], v[178:181], v[210:213], v[12:15]
	v_mfma_f32_16x16x32_bf16 v[48:51], v[214:217], v[182:185], v[48:51]
	v_mfma_f32_16x16x32_bf16 v[40:43], v[222:225], v[182:185], v[40:43]
	v_mfma_f32_16x16x32_bf16 v[32:35], v[214:217], v[190:193], v[32:35]
	v_mfma_f32_16x16x32_bf16 v[24:27], v[222:225], v[190:193], v[24:27]
	v_mfma_f32_16x16x32_bf16 v[16:19], v[214:217], v[198:201], v[16:19]
	v_mfma_f32_16x16x32_bf16 v[8:11], v[222:225], v[198:201], v[8:11]
	v_mfma_f32_16x16x32_bf16 v[4:7], v[214:217], v[206:209], v[4:7]
	v_mfma_f32_16x16x32_bf16 v[0:3], v[222:225], v[206:209], v[0:3]
	v_mfma_f32_16x16x32_bf16 v[48:51], v[218:221], v[186:189], v[48:51]
	v_mfma_f32_16x16x32_bf16 v[40:43], v[226:229], v[186:189], v[40:43]
	v_mfma_f32_16x16x32_bf16 v[32:35], v[218:221], v[194:197], v[32:35]
	v_mfma_f32_16x16x32_bf16 v[24:27], v[226:229], v[194:197], v[24:27]
	v_mfma_f32_16x16x32_bf16 v[16:19], v[218:221], v[202:205], v[16:19]
	v_mfma_f32_16x16x32_bf16 v[8:11], v[226:229], v[202:205], v[8:11]
	v_mfma_f32_16x16x32_bf16 v[4:7], v[218:221], v[210:213], v[4:7]
	v_mfma_f32_16x16x32_bf16 v[0:3], v[226:229], v[210:213], v[0:3]
	s_nop 0
	s_barrier
	s_add_i32 s84, 0, 0x18000
	v_add_u32_e32 v173, s84, v168
	ds_read_b128 v[150:153], v173
	ds_read_b128 v[154:157], v173 offset:1024
	ds_read_b128 v[174:177], v173 offset:2048
	ds_read_b128 v[178:181], v173 offset:3072
	s_add_u32 s56, s56, 0x160000
	s_addc_u32 s57, s57, 0
	s_mov_b32 m0, s58
	v_lshl_add_u64 v[214:215], s[56:57], 0, v[136:137]
	ds_read_b128 v[182:185], v171 offset:32768
	ds_read_b128 v[186:189], v171 offset:33792
	ds_read_b128 v[190:193], v171 offset:34816
	ds_read_b128 v[194:197], v171 offset:35840
	ds_read_b128 v[198:201], v171 offset:36864
	ds_read_b128 v[202:205], v171 offset:37888
	ds_read_b128 v[206:209], v171 offset:38912
	ds_read_b128 v[210:213], v171 offset:39936
	global_load_lds_dwordx4 v[214:215], off
	v_lshl_add_u64 v[214:215], s[56:57], 0, v[140:141]
	s_mov_b32 m0, s59
	s_nop 0
	global_load_lds_dwordx4 v[214:215], off
	s_add_i32 s56, 0, 0x1c000
	v_add_u32_e32 v173, s56, v168
	ds_read_b128 v[214:217], v173
	ds_read_b128 v[218:221], v173 offset:1024
	ds_read_b128 v[222:225], v173 offset:2048
	ds_read_b128 v[226:229], v173 offset:3072
	s_waitcnt vmcnt(8) lgkmcnt(0)
	s_barrier
	s_nop 0
	v_mfma_f32_16x16x32_bf16 v[124:127], v[150:153], v[182:185], v[124:127]
	v_mfma_f32_16x16x32_bf16 v[120:123], v[174:177], v[182:185], v[120:123]
	v_mfma_f32_16x16x32_bf16 v[116:119], v[150:153], v[190:193], v[116:119]
	v_mfma_f32_16x16x32_bf16 v[108:111], v[174:177], v[190:193], v[108:111]
	v_mfma_f32_16x16x32_bf16 v[100:103], v[150:153], v[198:201], v[100:103]
	v_mfma_f32_16x16x32_bf16 v[92:95], v[174:177], v[198:201], v[92:95]
	v_mfma_f32_16x16x32_bf16 v[84:87], v[150:153], v[206:209], v[84:87]
	v_mfma_f32_16x16x32_bf16 v[76:79], v[174:177], v[206:209], v[76:79]
	v_mfma_f32_16x16x32_bf16 v[124:127], v[154:157], v[186:189], v[124:127]
	v_mfma_f32_16x16x32_bf16 v[120:123], v[178:181], v[186:189], v[120:123]
	v_mfma_f32_16x16x32_bf16 v[116:119], v[154:157], v[194:197], v[116:119]
	v_mfma_f32_16x16x32_bf16 v[108:111], v[178:181], v[194:197], v[108:111]
	v_mfma_f32_16x16x32_bf16 v[100:103], v[154:157], v[202:205], v[100:103]
	v_mfma_f32_16x16x32_bf16 v[92:95], v[178:181], v[202:205], v[92:95]
	v_mfma_f32_16x16x32_bf16 v[84:87], v[154:157], v[210:213], v[84:87]
	v_mfma_f32_16x16x32_bf16 v[76:79], v[178:181], v[210:213], v[76:79]
	v_mfma_f32_16x16x32_bf16 v[112:115], v[214:217], v[182:185], v[112:115]
	v_mfma_f32_16x16x32_bf16 v[104:107], v[222:225], v[182:185], v[104:107]
	v_mfma_f32_16x16x32_bf16 v[96:99], v[214:217], v[190:193], v[96:99]
	v_mfma_f32_16x16x32_bf16 v[88:91], v[222:225], v[190:193], v[88:91]
	v_mfma_f32_16x16x32_bf16 v[80:83], v[214:217], v[198:201], v[80:83]
	v_mfma_f32_16x16x32_bf16 v[72:75], v[222:225], v[198:201], v[72:75]
	v_mfma_f32_16x16x32_bf16 v[68:71], v[214:217], v[206:209], v[68:71]
	v_mfma_f32_16x16x32_bf16 v[64:67], v[222:225], v[206:209], v[64:67]
	v_mfma_f32_16x16x32_bf16 v[112:115], v[218:221], v[186:189], v[112:115]
	v_mfma_f32_16x16x32_bf16 v[104:107], v[226:229], v[186:189], v[104:107]
	v_mfma_f32_16x16x32_bf16 v[96:99], v[218:221], v[194:197], v[96:99]
	v_mfma_f32_16x16x32_bf16 v[88:91], v[226:229], v[194:197], v[88:91]
	v_mfma_f32_16x16x32_bf16 v[80:83], v[218:221], v[202:205], v[80:83]
	v_mfma_f32_16x16x32_bf16 v[72:75], v[226:229], v[202:205], v[72:75]
	v_mfma_f32_16x16x32_bf16 v[68:71], v[218:221], v[210:213], v[68:71]
	v_mfma_f32_16x16x32_bf16 v[64:67], v[226:229], v[210:213], v[64:67]
	s_nop 0
	s_barrier
; #define PG8_STAGE(bufoff, gbase, voff) do { _Pragma("unroll") for (int _i = 0; _i < 2; ++_i) \
;         __builtin_amdgcn_global_load_lds((const unsigned*)((const char*)(gbase) + (voff)[_i]), (LAS unsigned*)(lds + (bufoff) + ldsw + _i * 8192), 16, 0, 0); } while (0)
; #define PG8_MMA(ai, bj, At, Bt) do { __builtin_amdgcn_s_setprio(1); _Pragma("unroll") for (int m = 0; m < 4; ++m) _Pragma("unroll") for (int n = 0; n < 2; ++n) _Pragma("unroll") for (int k = 0; k < 2; ++k) \
;         acc[ai][bj][m][n] = __builtin_amdgcn_mfma_f32_16x16x32_bf16(Bt[n][k], At[m][k], acc[ai][bj][m][n], 0, 0, 0); __builtin_amdgcn_s_setprio(0); } while (0)
; #define PG8_WAIT_V(n) asm volatile("s_waitcnt vmcnt(" #n ")" ::: "memory")
; #define PG8_BAR __builtin_amdgcn_s_barrier()
; template <class Epi>
; __device__ __forceinline__ void gemm_phase(LAS unsigned char* lds, const Gemm g, const StaticOrder& S, const Epi& E) {
;     ...
;         for (int t = 0; t < nt; t += 2) {
;     ...
;             PG8_STAGE(PG8_SB(1, 1), b3 + hstepB, voffB);
;             PG8_WAIT_V(6); PG8_BAR; PG8_MMA(1, 1, At, B1); PG8_BAR;
	s_add_i32 s57, s84, s21
	v_lshl_add_u64 v[158:159], v[158:159], 0, s[22:23]
	s_mov_b32 m0, s57
	global_load_lds_dwordx4 v[158:159], off
	v_lshl_add_u64 v[158:159], v[230:231], 0, s[22:23]
	s_add_i32 m0, s57, 0x2000
	s_nop 0
	global_load_lds_dwordx4 v[158:159], off
	s_mov_b32 m0, s60
	v_lshl_add_u64 v[158:159], v[232:233], 0, s[22:23]
	ds_read_b128 v[182:185], v171 offset:49152
	ds_read_b128 v[186:189], v171 offset:50176
	ds_read_b128 v[190:193], v171 offset:51200
	ds_read_b128 v[194:197], v171 offset:52224
	ds_read_b128 v[198:201], v171 offset:53248
	ds_read_b128 v[202:205], v171 offset:54272
	ds_read_b128 v[206:209], v171 offset:55296
	ds_read_b128 v[210:213], v171 offset:56320
	global_load_lds_dwordx4 v[158:159], off
	v_lshl_add_u64 v[158:159], v[234:235], 0, s[22:23]
	s_mov_b32 m0, s61
	s_nop 0
	global_load_lds_dwordx4 v[158:159], off
	s_add_u32 s54, s54, 0xb0080
	s_addc_u32 s55, s55, 0
	s_add_i32 s56, s56, s21
	v_lshl_add_u64 v[240:241], s[54:55], 0, v[138:139]
	s_mov_b32 m0, s56
	s_nop 0
	global_load_lds_dwordx4 v[240:241], off
	v_lshl_add_u64 v[240:241], s[54:55], 0, v[142:143]
	s_add_i32 m0, s56, 0x2000
	s_nop 0
	global_load_lds_dwordx4 v[240:241], off
	s_waitcnt vmcnt(8) lgkmcnt(0)
	s_barrier
	s_nop 0
	v_mfma_f32_16x16x32_bf16 v[60:63], v[150:153], v[182:185], v[60:63]
	v_mfma_f32_16x16x32_bf16 v[56:59], v[174:177], v[182:185], v[56:59]
	v_mfma_f32_16x16x32_bf16 v[52:55], v[150:153], v[190:193], v[52:55]
	v_mfma_f32_16x16x32_bf16 v[44:47], v[174:177], v[190:193], v[44:47]
	v_mfma_f32_16x16x32_bf16 v[36:39], v[150:153], v[198:201], v[36:39]
	v_mfma_f32_16x16x32_bf16 v[28:31], v[174:177], v[198:201], v[28:31]
	v_mfma_f32_16x16x32_bf16 v[20:23], v[150:153], v[206:209], v[20:23]
	v_mfma_f32_16x16x32_bf16 v[12:15], v[174:177], v[206:209], v[12:15]
	v_mfma_f32_16x16x32_bf16 v[60:63], v[154:157], v[186:189], v[60:63]
	v_mfma_f32_16x16x32_bf16 v[56:59], v[178:181], v[186:189], v[56:59]
	v_mfma_f32_16x16x32_bf16 v[52:55], v[154:157], v[194:197], v[52:55]
	v_mfma_f32_16x16x32_bf16 v[44:47], v[178:181], v[194:197], v[44:47]
	v_mfma_f32_16x16x32_bf16 v[36:39], v[154:157], v[202:205], v[36:39]
	v_mfma_f32_16x16x32_bf16 v[28:31], v[178:181], v[202:205], v[28:31]
	v_mfma_f32_16x16x32_bf16 v[20:23], v[154:157], v[210:213], v[20:23]
	v_mfma_f32_16x16x32_bf16 v[12:15], v[178:181], v[210:213], v[12:15]
	v_mfma_f32_16x16x32_bf16 v[48:51], v[214:217], v[182:185], v[48:51]
	v_mfma_f32_16x16x32_bf16 v[40:43], v[222:225], v[182:185], v[40:43]
	v_mfma_f32_16x16x32_bf16 v[32:35], v[214:217], v[190:193], v[32:35]
	v_mfma_f32_16x16x32_bf16 v[24:27], v[222:225], v[190:193], v[24:27]
	v_mfma_f32_16x16x32_bf16 v[16:19], v[214:217], v[198:201], v[16:19]
	v_mfma_f32_16x16x32_bf16 v[8:11], v[222:225], v[198:201], v[8:11]
	v_mfma_f32_16x16x32_bf16 v[4:7], v[214:217], v[206:209], v[4:7]
	v_mfma_f32_16x16x32_bf16 v[0:3], v[222:225], v[206:209], v[0:3]
	v_mfma_f32_16x16x32_bf16 v[48:51], v[218:221], v[186:189], v[48:51]
	v_mfma_f32_16x16x32_bf16 v[40:43], v[226:229], v[186:189], v[40:43]
	v_mfma_f32_16x16x32_bf16 v[32:35], v[218:221], v[194:197], v[32:35]
	v_mfma_f32_16x16x32_bf16 v[24:27], v[226:229], v[194:197], v[24:27]
	v_mfma_f32_16x16x32_bf16 v[16:19], v[218:221], v[202:205], v[16:19]
	v_mfma_f32_16x16x32_bf16 v[8:11], v[226:229], v[202:205], v[8:11]
	v_mfma_f32_16x16x32_bf16 v[4:7], v[218:221], v[210:213], v[4:7]
	v_mfma_f32_16x16x32_bf16 v[0:3], v[226:229], v[210:213], v[0:3]
	s_nop 0
	s_add_u32 s46, s46, 0x100
	s_addc_u32 s47, s47, 0
	s_add_u32 s41, s41, 0x100
	s_addc_u32 s82, s82, 0
	s_cmp_ge_i32 s83, s81
	s_mov_b32 s54, s83
	s_barrier
;     __device__ __forceinline__ void operator()(const f32x4 (&acc)[2][2][4][2], const Unit& u, int wr, int wc, int fr, int fq) const {
;         const int row0 = u.pm * BM + wr * 64 + fr, col0 = u.pn * BM + wc * 32 + 8 * fq;
;         if (u.part) {
;             float* base = tailacc + (size_t)(u.part - 1) * slab - (size_t)tail_row0 * tail_ld;
; #pragma unroll
;             for (int ai = 0; ai < 2; ++ai)
; #pragma unroll
;                 for (int m = 0; m < 4; ++m) { float* rowp = base + (size_t)(row0 + ai * HALF + m * 16) * tail_ld + col0;
; #pragma unroll
;                     for (int bj = 0; bj < 2; ++bj)
; #pragma unroll
;                         for (int n = 0; n < 2; ++n) *(f32x4*)(rowp + bj * HALF + 4 * n) = acc[ai][bj][m][n]; }
	s_cbranch_scc0 .LBB0_910
	v_lshl_add_u32 v158, s78, 8, v167
	v_lshl_or_b32 v150, s79, 8, v169
	v_or_b32_e32 v156, 16, v158
	v_or_b32_e32 v154, 32, v158
	v_or_b32_e32 v152, 48, v158
	s_cmp_lg_u32 s80, 0
	v_ashrrev_i32_e32 v151, 31, v150
	v_ashrrev_i32_e32 v159, 31, v158
	v_ashrrev_i32_e32 v157, 31, v156
	v_ashrrev_i32_e32 v155, 31, v154
	v_ashrrev_i32_e32 v153, 31, v152
	s_cbranch_scc0 .LBB0_913
	s_add_i32 s18, s80, -1
	s_lshl_b64 s[46:47], s[18:19], 21
	s_add_u32 s46, s92, s46
	s_addc_u32 s47, s93, s47
	v_lshl_add_u64 v[174:175], v[150:151], 2, s[46:47]
	s_brev_b32 s46, 63
	s_mov_b32 s47, -1
	v_lshl_add_u64 v[174:175], v[174:175], 0, s[46:47]
	v_lshlrev_b64 v[176:177], 12, v[158:159]
	v_lshlrev_b64 v[178:179], 12, v[156:157]
	v_lshl_add_u64 v[176:177], v[174:175], 0, v[176:177]
	v_lshl_add_u64 v[178:179], v[174:175], 0, v[178:179]
	global_store_dwordx4 v[176:177], v[124:127], off
	global_store_dwordx4 v[176:177], v[120:123], off offset:16
	global_store_dwordx4 v[176:177], v[112:115], off offset:512
	global_store_dwordx4 v[176:177], v[104:107], off offset:528
	global_store_dwordx4 v[178:179], v[116:119], off
	global_store_dwordx4 v[178:179], v[108:111], off offset:16
	global_store_dwordx4 v[178:179], v[96:99], off offset:512
	global_store_dwordx4 v[178:179], v[88:91], off offset:528
	v_lshlrev_b64 v[178:179], 12, v[154:155]
	v_lshl_add_u64 v[178:179], v[174:175], 0, v[178:179]
	global_store_dwordx4 v[178:179], v[100:103], off
	global_store_dwordx4 v[178:179], v[92:95], off offset:16
	global_store_dwordx4 v[178:179], v[80:83], off offset:512
	global_store_dwordx4 v[178:179], v[72:75], off offset:528
	v_lshlrev_b64 v[178:179], 12, v[152:153]
	s_mov_b32 s18, 0x80000
	v_lshl_add_u64 v[174:175], v[174:175], 0, v[178:179]
	v_add_co_u32_e32 v178, vcc, s18, v176
	s_mov_b64 s[46:47], 0x80000
	s_nop 0
	v_addc_co_u32_e32 v179, vcc, 0, v177, vcc
	global_store_dwordx4 v[174:175], v[84:87], off
	global_store_dwordx4 v[174:175], v[76:79], off offset:16
	global_store_dwordx4 v[174:175], v[68:71], off offset:512
	global_store_dwordx4 v[174:175], v[64:67], off offset:528
	v_lshl_add_u64 v[174:175], v[176:177], 0, s[46:47]
	global_store_dwordx4 v[178:179], v[60:63], off
	global_store_dwordx4 v[174:175], v[56:59], off offset:16
	global_store_dwordx4 v[174:175], v[48:51], off offset:512
	global_store_dwordx4 v[174:175], v[40:43], off offset:528
	v_add_co_u32_e32 v178, vcc, s67, v176
	s_mov_b64 s[46:47], 0x90000
	s_nop 0
	v_addc_co_u32_e32 v179, vcc, 0, v177, vcc
	v_lshl_add_u64 v[174:175], v[176:177], 0, s[46:47]
	global_store_dwordx4 v[178:179], v[52:55], off
	global_store_dwordx4 v[174:175], v[44:47], off offset:16
	global_store_dwordx4 v[174:175], v[32:35], off offset:512
	global_store_dwordx4 v[174:175], v[24:27], off offset:528
	v_add_co_u32_e32 v178, vcc, s68, v176
	v_lshl_add_u64 v[174:175], v[176:177], 0, s[24:25]
	s_nop 0
	v_addc_co_u32_e32 v179, vcc, 0, v177, vcc
	s_mov_b64 s[46:47], 0xb0000
	global_store_dwordx4 v[178:179], v[36:39], off
	global_store_dwordx4 v[174:175], v[28:31], off offset:16
	global_store_dwordx4 v[174:175], v[16:19], off offset:512
	global_store_dwordx4 v[174:175], v[8:11], off offset:528
	v_lshl_add_u64 v[174:175], v[176:177], 0, s[46:47]
	v_add_co_u32_e32 v176, vcc, 0xb0000, v176
	s_nop 1
	v_addc_co_u32_e32 v177, vcc, 0, v177, vcc
	global_store_dwordx4 v[176:177], v[20:23], off
	global_store_dwordx4 v[174:175], v[12:15], off offset:16
	global_store_dwordx4 v[174:175], v[4:7], off offset:512
	global_store_dwordx4 v[174:175], v[0:3], off offset:528
	s_cbranch_execnz .LBB0_895
	s_branch .LBB0_894

; #define PG8_STAGE(bufoff, gbase, voff) do { _Pragma("unroll") for (int _i = 0; _i < 2; ++_i) \
;         __builtin_amdgcn_global_load_lds((const unsigned*)((const char*)(gbase) + (voff)[_i]), (LAS unsigned*)(lds + (bufoff) + ldsw + _i * 8192), 16, 0, 0); } while (0)
; #define PG8_LDA(dst, b, h) do { _Pragma("unroll") for (int m = 0; m < 4; ++m) _Pragma("unroll") for (int k = 0; k < 2; ++k) dst[m][k] = *(const LAS bf16x8*)(lds + PG8_SA(b, h) + aoff + m * 2048 + k * 1024); } while (0)
; #define PG8_LDB(dst, b, h) do { _Pragma("unroll") for (int n = 0; n < 2; ++n) _Pragma("unroll") for (int k = 0; k < 2; ++k) dst[n][k] = *(const LAS bf16x8*)(lds + PG8_SB(b, h) + boff + n * 2048 + k * 1024); } while (0)
; #define PG8_MMA(ai, bj, At, Bt) do { __builtin_amdgcn_s_setprio(1); _Pragma("unroll") for (int m = 0; m < 4; ++m) _Pragma("unroll") for (int n = 0; n < 2; ++n) _Pragma("unroll") for (int k = 0; k < 2; ++k) \
;         acc[ai][bj][m][n] = __builtin_amdgcn_mfma_f32_16x16x32_bf16(Bt[n][k], At[m][k], acc[ai][bj][m][n], 0, 0, 0); __builtin_amdgcn_s_setprio(0); } while (0)
; #define PG8_WAIT_V(n) asm volatile("s_waitcnt vmcnt(" #n ")" ::: "memory")
; #define PG8_WAIT_L(n) asm volatile("s_waitcnt lgkmcnt(" #n ")" ::: "memory")
; #define PG8_BAR __builtin_amdgcn_s_barrier()
; #define PG8_SCHED __builtin_amdgcn_sched_barrier(0)
; template <class Epi>
; __device__ __forceinline__ void gemm_phase(LAS unsigned char* lds, const Gemm g, const StaticOrder& S, const Epi& E) {
;     ...
;             PG8_LDB(B0, 0, 0); PG8_SCHED; PG8_LDA(At, 0, 0); PG8_STAGE(PG8_SA(1, 1), a1 + hstepA, voffA);
;             PG8_WAIT_L(8); PG8_BAR; PG8_WAIT_L(0); PG8_MMA(0, 0, At, B0); PG8_BAR; PG8_SCHED;
;             PG8_LDB(B1, 0, 1); PG8_STAGE(PG8_SB(0, 0), b2, voffB);
;             PG8_BAR; PG8_WAIT_L(0); PG8_MMA(0, 1, At, B1); PG8_BAR;
;             PG8_LDA(At, 0, 1); PG8_STAGE(PG8_SA(0, 0), a2, voffA);
;             PG8_BAR; PG8_WAIT_L(0); PG8_MMA(1, 0, At, B0); PG8_BAR; PG8_SCHED;
;             PG8_STAGE(PG8_SB(0, 1), b2 + hstepB, voffB);
;             PG8_WAIT_V(6); PG8_BAR; PG8_MMA(1, 1, At, B1); PG8_BAR;
.LBB0_1146:
	ds_read_b128 v[150:153], v129
	ds_read_b128 v[154:157], v129 offset:1024
	ds_read_b128 v[158:161], v129 offset:2048
	ds_read_b128 v[166:169], v129 offset:3072
	s_add_i32 s77, s45, 2
	s_add_u32 s54, s50, 0xfffc0080
	s_addc_u32 s55, s51, -1
	s_cmp_eq_u32 s39, s45
	s_cselect_b32 s57, s49, s55
	s_cselect_b32 s56, s48, s54
	s_cselect_b32 s55, s1, s43
	s_cselect_b32 s54, s0, s41
	v_lshl_add_u64 v[202:203], s[50:51], 0, v[144:145]
	s_add_i32 m0, s33, 0xc000
	ds_read_b128 v[170:173], v163
	ds_read_b128 v[174:177], v163 offset:1024
	ds_read_b128 v[178:181], v163 offset:2048
	ds_read_b128 v[182:185], v163 offset:3072
	ds_read_b128 v[186:189], v163 offset:4096
	ds_read_b128 v[190:193], v163 offset:5120
	ds_read_b128 v[194:197], v163 offset:6144
	ds_read_b128 v[198:201], v163 offset:7168
	global_load_lds_dwordx4 v[202:203], off
	v_lshl_add_u64 v[202:203], s[50:51], 0, v[146:147]
	s_add_i32 m0, s33, 0xe000
	s_nop 0
	global_load_lds_dwordx4 v[202:203], off
	ds_read_b128 v[202:205], v164
	ds_read_b128 v[206:209], v164 offset:1024
	ds_read_b128 v[210:213], v164 offset:2048
	ds_read_b128 v[214:217], v164 offset:3072
	s_waitcnt vmcnt(8) lgkmcnt(0)
	s_barrier
	s_nop 0
	v_mfma_f32_16x16x32_bf16 v[124:127], v[150:153], v[170:173], v[124:127]
	v_mfma_f32_16x16x32_bf16 v[120:123], v[158:161], v[170:173], v[120:123]
	v_mfma_f32_16x16x32_bf16 v[116:119], v[150:153], v[178:181], v[116:119]
	v_mfma_f32_16x16x32_bf16 v[108:111], v[158:161], v[178:181], v[108:111]
	v_mfma_f32_16x16x32_bf16 v[100:103], v[150:153], v[186:189], v[100:103]
	v_mfma_f32_16x16x32_bf16 v[92:95], v[158:161], v[186:189], v[92:95]
	v_mfma_f32_16x16x32_bf16 v[84:87], v[150:153], v[194:197], v[84:87]
	v_mfma_f32_16x16x32_bf16 v[76:79], v[158:161], v[194:197], v[76:79]
	v_mfma_f32_16x16x32_bf16 v[124:127], v[154:157], v[174:177], v[124:127]
	v_mfma_f32_16x16x32_bf16 v[120:123], v[166:169], v[174:177], v[120:123]
	v_mfma_f32_16x16x32_bf16 v[116:119], v[154:157], v[182:185], v[116:119]
	v_mfma_f32_16x16x32_bf16 v[108:111], v[166:169], v[182:185], v[108:111]
	v_mfma_f32_16x16x32_bf16 v[100:103], v[154:157], v[190:193], v[100:103]
	v_mfma_f32_16x16x32_bf16 v[92:95], v[166:169], v[190:193], v[92:95]
	v_mfma_f32_16x16x32_bf16 v[84:87], v[154:157], v[198:201], v[84:87]
	v_mfma_f32_16x16x32_bf16 v[76:79], v[166:169], v[198:201], v[76:79]
	v_mfma_f32_16x16x32_bf16 v[112:115], v[202:205], v[170:173], v[112:115]
	v_mfma_f32_16x16x32_bf16 v[104:107], v[210:213], v[170:173], v[104:107]
	v_mfma_f32_16x16x32_bf16 v[96:99], v[202:205], v[178:181], v[96:99]
	v_mfma_f32_16x16x32_bf16 v[88:91], v[210:213], v[178:181], v[88:91]
	v_mfma_f32_16x16x32_bf16 v[80:83], v[202:205], v[186:189], v[80:83]
	v_mfma_f32_16x16x32_bf16 v[72:75], v[210:213], v[186:189], v[72:75]
	v_mfma_f32_16x16x32_bf16 v[68:71], v[202:205], v[194:197], v[68:71]
	v_mfma_f32_16x16x32_bf16 v[64:67], v[210:213], v[194:197], v[64:67]
	v_mfma_f32_16x16x32_bf16 v[112:115], v[206:209], v[174:177], v[112:115]
	v_mfma_f32_16x16x32_bf16 v[104:107], v[214:217], v[174:177], v[104:107]
	v_mfma_f32_16x16x32_bf16 v[96:99], v[206:209], v[182:185], v[96:99]
	v_mfma_f32_16x16x32_bf16 v[88:91], v[214:217], v[182:185], v[88:91]
	v_mfma_f32_16x16x32_bf16 v[80:83], v[206:209], v[190:193], v[80:83]
	v_mfma_f32_16x16x32_bf16 v[72:75], v[214:217], v[190:193], v[72:75]
	v_mfma_f32_16x16x32_bf16 v[68:71], v[206:209], v[198:201], v[68:71]
	v_mfma_f32_16x16x32_bf16 v[64:67], v[214:217], v[198:201], v[64:67]
	s_nop 0
	s_barrier
	s_add_i32 s45, s66, s21
	v_lshl_add_u64 v[218:219], s[54:55], 0, v[138:139]
	s_mov_b32 m0, s45
	global_load_lds_dwordx4 v[218:219], off
	v_lshl_add_u64 v[220:221], s[54:55], 0, v[142:143]
	s_add_i32 m0, s45, 0x2000
	s_nop 0
	global_load_lds_dwordx4 v[220:221], off
	s_mov_b32 m0, s33
	v_lshl_add_u64 v[222:223], s[56:57], 0, v[136:137]
	ds_read_b128 v[170:173], v163 offset:16384
	ds_read_b128 v[174:177], v163 offset:17408
	ds_read_b128 v[178:181], v163 offset:18432
	ds_read_b128 v[182:185], v163 offset:19456
	ds_read_b128 v[186:189], v163 offset:20480
	ds_read_b128 v[190:193], v163 offset:21504
	ds_read_b128 v[194:197], v163 offset:22528
	ds_read_b128 v[198:201], v163 offset:23552
	global_load_lds_dwordx4 v[222:223], off
	v_lshl_add_u64 v[224:225], s[56:57], 0, v[140:141]
	s_mov_b32 m0, s35
	s_nop 0
	global_load_lds_dwordx4 v[224:225], off
	s_add_u32 s78, s54, 0x40000
	s_addc_u32 s79, s55, 0
	s_add_i32 s45, s67, s21
	v_lshl_add_u64 v[240:241], s[78:79], 0, v[138:139]
	s_mov_b32 m0, s45
	s_nop 0
	global_load_lds_dwordx4 v[240:241], off
	v_lshl_add_u64 v[240:241], s[78:79], 0, v[142:143]
	s_add_i32 m0, s45, 0x2000
	s_nop 0
	global_load_lds_dwordx4 v[240:241], off
	s_waitcnt vmcnt(8) lgkmcnt(0)
	s_barrier
; #define PG8_STAGE(bufoff, gbase, voff) do { _Pragma("unroll") for (int _i = 0; _i < 2; ++_i) \
;         __builtin_amdgcn_global_load_lds((const unsigned*)((const char*)(gbase) + (voff)[_i]), (LAS unsigned*)(lds + (bufoff) + ldsw + _i * 8192), 16, 0, 0); } while (0)
; #define PG8_LDA(dst, b, h) do { _Pragma("unroll") for (int m = 0; m < 4; ++m) _Pragma("unroll") for (int k = 0; k < 2; ++k) dst[m][k] = *(const LAS bf16x8*)(lds + PG8_SA(b, h) + aoff + m * 2048 + k * 1024); } while (0)
; #define PG8_LDB(dst, b, h) do { _Pragma("unroll") for (int n = 0; n < 2; ++n) _Pragma("unroll") for (int k = 0; k < 2; ++k) dst[n][k] = *(const LAS bf16x8*)(lds + PG8_SB(b, h) + boff + n * 2048 + k * 1024); } while (0)
; #define PG8_MMA(ai, bj, At, Bt) do { __builtin_amdgcn_s_setprio(1); _Pragma("unroll") for (int m = 0; m < 4; ++m) _Pragma("unroll") for (int n = 0; n < 2; ++n) _Pragma("unroll") for (int k = 0; k < 2; ++k) \
;         acc[ai][bj][m][n] = __builtin_amdgcn_mfma_f32_16x16x32_bf16(Bt[n][k], At[m][k], acc[ai][bj][m][n], 0, 0, 0); __builtin_amdgcn_s_setprio(0); } while (0)
; #define PG8_WAIT_L(n) asm volatile("s_waitcnt lgkmcnt(" #n ")" ::: "memory")
; #define PG8_BAR __builtin_amdgcn_s_barrier()
; #define PG8_SCHED __builtin_amdgcn_sched_barrier(0)
; template <class Epi>
; __device__ __forceinline__ void gemm_phase(LAS unsigned char* lds, const Gemm g, const StaticOrder& S, const Epi& E) {
;     ...
;             PG8_LDB(B0, 1, 0); PG8_SCHED; PG8_LDA(At, 1, 0); PG8_STAGE(PG8_SA(0, 1), a2 + hstepA, voffA);
;             PG8_WAIT_L(8); PG8_BAR; PG8_WAIT_L(0); PG8_MMA(0, 0, At, B0); PG8_BAR; PG8_SCHED;
;             PG8_LDB(B1, 1, 1); PG8_STAGE(PG8_SB(1, 0), b3, voffB);
;             PG8_BAR; PG8_WAIT_L(0); PG8_MMA(0, 1, At, B1); PG8_BAR;
;             PG8_LDA(At, 1, 1); PG8_STAGE(PG8_SA(1, 0), a3, voffA);
;             PG8_BAR; PG8_WAIT_L(0); PG8_MMA(1, 0, At, B0); PG8_BAR; PG8_SCHED;
	s_nop 0
	v_mfma_f32_16x16x32_bf16 v[60:63], v[150:153], v[170:173], v[60:63]
	v_mfma_f32_16x16x32_bf16 v[56:59], v[158:161], v[170:173], v[56:59]
	v_mfma_f32_16x16x32_bf16 v[52:55], v[150:153], v[178:181], v[52:55]
	v_mfma_f32_16x16x32_bf16 v[44:47], v[158:161], v[178:181], v[44:47]
	v_mfma_f32_16x16x32_bf16 v[36:39], v[150:153], v[186:189], v[36:39]
	v_mfma_f32_16x16x32_bf16 v[28:31], v[158:161], v[186:189], v[28:31]
	v_mfma_f32_16x16x32_bf16 v[20:23], v[150:153], v[194:197], v[20:23]
	v_mfma_f32_16x16x32_bf16 v[12:15], v[158:161], v[194:197], v[12:15]
	v_mfma_f32_16x16x32_bf16 v[60:63], v[154:157], v[174:177], v[60:63]
	v_mfma_f32_16x16x32_bf16 v[56:59], v[166:169], v[174:177], v[56:59]
	v_mfma_f32_16x16x32_bf16 v[52:55], v[154:157], v[182:185], v[52:55]
	v_mfma_f32_16x16x32_bf16 v[44:47], v[166:169], v[182:185], v[44:47]
	v_mfma_f32_16x16x32_bf16 v[36:39], v[154:157], v[190:193], v[36:39]
	v_mfma_f32_16x16x32_bf16 v[28:31], v[166:169], v[190:193], v[28:31]
	v_mfma_f32_16x16x32_bf16 v[20:23], v[154:157], v[198:201], v[20:23]
	v_mfma_f32_16x16x32_bf16 v[12:15], v[166:169], v[198:201], v[12:15]
	v_mfma_f32_16x16x32_bf16 v[48:51], v[202:205], v[170:173], v[48:51]
	v_mfma_f32_16x16x32_bf16 v[40:43], v[210:213], v[170:173], v[40:43]
	v_mfma_f32_16x16x32_bf16 v[32:35], v[202:205], v[178:181], v[32:35]
	v_mfma_f32_16x16x32_bf16 v[24:27], v[210:213], v[178:181], v[24:27]
	v_mfma_f32_16x16x32_bf16 v[16:19], v[202:205], v[186:189], v[16:19]
	v_mfma_f32_16x16x32_bf16 v[8:11], v[210:213], v[186:189], v[8:11]
	v_mfma_f32_16x16x32_bf16 v[4:7], v[202:205], v[194:197], v[4:7]
	v_mfma_f32_16x16x32_bf16 v[0:3], v[210:213], v[194:197], v[0:3]
	v_mfma_f32_16x16x32_bf16 v[48:51], v[206:209], v[174:177], v[48:51]
	v_mfma_f32_16x16x32_bf16 v[40:43], v[214:217], v[174:177], v[40:43]
	v_mfma_f32_16x16x32_bf16 v[32:35], v[206:209], v[182:185], v[32:35]
	v_mfma_f32_16x16x32_bf16 v[24:27], v[214:217], v[182:185], v[24:27]
	v_mfma_f32_16x16x32_bf16 v[16:19], v[206:209], v[190:193], v[16:19]
	v_mfma_f32_16x16x32_bf16 v[8:11], v[214:217], v[190:193], v[8:11]
	v_mfma_f32_16x16x32_bf16 v[4:7], v[206:209], v[198:201], v[4:7]
	v_mfma_f32_16x16x32_bf16 v[0:3], v[214:217], v[198:201], v[0:3]
	s_nop 0
	s_barrier
	s_add_i32 s45, 0, 0x18000
	v_add_u32_e32 v165, s45, v135
	ds_read_b128 v[150:153], v165
	ds_read_b128 v[154:157], v165 offset:1024
	ds_read_b128 v[158:161], v165 offset:2048
	ds_read_b128 v[166:169], v165 offset:3072
	s_add_u32 s56, s56, 0x40000
	s_addc_u32 s57, s57, 0
	s_mov_b32 m0, s58
	v_lshl_add_u64 v[202:203], s[56:57], 0, v[136:137]
	ds_read_b128 v[170:173], v163 offset:32768
	ds_read_b128 v[174:177], v163 offset:33792
	ds_read_b128 v[178:181], v163 offset:34816
	ds_read_b128 v[182:185], v163 offset:35840
	ds_read_b128 v[186:189], v163 offset:36864
	ds_read_b128 v[190:193], v163 offset:37888
	ds_read_b128 v[194:197], v163 offset:38912
	ds_read_b128 v[198:201], v163 offset:39936
	global_load_lds_dwordx4 v[202:203], off
	v_lshl_add_u64 v[202:203], s[56:57], 0, v[140:141]
	s_mov_b32 m0, s59
	s_nop 0
	global_load_lds_dwordx4 v[202:203], off
	s_add_i32 s56, 0, 0x1c000
	v_add_u32_e32 v165, s56, v135
	ds_read_b128 v[202:205], v165
	ds_read_b128 v[206:209], v165 offset:1024
	ds_read_b128 v[210:213], v165 offset:2048
	ds_read_b128 v[214:217], v165 offset:3072
	s_waitcnt vmcnt(8) lgkmcnt(0)
	s_barrier
	s_nop 0
	v_mfma_f32_16x16x32_bf16 v[124:127], v[150:153], v[170:173], v[124:127]
	v_mfma_f32_16x16x32_bf16 v[120:123], v[158:161], v[170:173], v[120:123]
	v_mfma_f32_16x16x32_bf16 v[116:119], v[150:153], v[178:181], v[116:119]
	v_mfma_f32_16x16x32_bf16 v[108:111], v[158:161], v[178:181], v[108:111]
	v_mfma_f32_16x16x32_bf16 v[100:103], v[150:153], v[186:189], v[100:103]
	v_mfma_f32_16x16x32_bf16 v[92:95], v[158:161], v[186:189], v[92:95]
	v_mfma_f32_16x16x32_bf16 v[84:87], v[150:153], v[194:197], v[84:87]
	v_mfma_f32_16x16x32_bf16 v[76:79], v[158:161], v[194:197], v[76:79]
	v_mfma_f32_16x16x32_bf16 v[124:127], v[154:157], v[174:177], v[124:127]
	v_mfma_f32_16x16x32_bf16 v[120:123], v[166:169], v[174:177], v[120:123]
	v_mfma_f32_16x16x32_bf16 v[116:119], v[154:157], v[182:185], v[116:119]
	v_mfma_f32_16x16x32_bf16 v[108:111], v[166:169], v[182:185], v[108:111]
	v_mfma_f32_16x16x32_bf16 v[100:103], v[154:157], v[190:193], v[100:103]
	v_mfma_f32_16x16x32_bf16 v[92:95], v[166:169], v[190:193], v[92:95]
	v_mfma_f32_16x16x32_bf16 v[84:87], v[154:157], v[198:201], v[84:87]
	v_mfma_f32_16x16x32_bf16 v[76:79], v[166:169], v[198:201], v[76:79]
	v_mfma_f32_16x16x32_bf16 v[112:115], v[202:205], v[170:173], v[112:115]
	v_mfma_f32_16x16x32_bf16 v[104:107], v[210:213], v[170:173], v[104:107]
	v_mfma_f32_16x16x32_bf16 v[96:99], v[202:205], v[178:181], v[96:99]
	v_mfma_f32_16x16x32_bf16 v[88:91], v[210:213], v[178:181], v[88:91]
	v_mfma_f32_16x16x32_bf16 v[80:83], v[202:205], v[186:189], v[80:83]
	v_mfma_f32_16x16x32_bf16 v[72:75], v[210:213], v[186:189], v[72:75]
	v_mfma_f32_16x16x32_bf16 v[68:71], v[202:205], v[194:197], v[68:71]
	v_mfma_f32_16x16x32_bf16 v[64:67], v[210:213], v[194:197], v[64:67]
	v_mfma_f32_16x16x32_bf16 v[112:115], v[206:209], v[174:177], v[112:115]
	v_mfma_f32_16x16x32_bf16 v[104:107], v[214:217], v[174:177], v[104:107]
	v_mfma_f32_16x16x32_bf16 v[96:99], v[206:209], v[182:185], v[96:99]
	v_mfma_f32_16x16x32_bf16 v[88:91], v[214:217], v[182:185], v[88:91]
	v_mfma_f32_16x16x32_bf16 v[80:83], v[206:209], v[190:193], v[80:83]
	v_mfma_f32_16x16x32_bf16 v[72:75], v[214:217], v[190:193], v[72:75]
	v_mfma_f32_16x16x32_bf16 v[68:71], v[206:209], v[198:201], v[68:71]
	v_mfma_f32_16x16x32_bf16 v[64:67], v[214:217], v[198:201], v[64:67]
	s_nop 0
	s_barrier
; #define PG8_STAGE(bufoff, gbase, voff) do { _Pragma("unroll") for (int _i = 0; _i < 2; ++_i) \
;         __builtin_amdgcn_global_load_lds((const unsigned*)((const char*)(gbase) + (voff)[_i]), (LAS unsigned*)(lds + (bufoff) + ldsw + _i * 8192), 16, 0, 0); } while (0)
; #define PG8_MMA(ai, bj, At, Bt) do { __builtin_amdgcn_s_setprio(1); _Pragma("unroll") for (int m = 0; m < 4; ++m) _Pragma("unroll") for (int n = 0; n < 2; ++n) _Pragma("unroll") for (int k = 0; k < 2; ++k) \
;         acc[ai][bj][m][n] = __builtin_amdgcn_mfma_f32_16x16x32_bf16(Bt[n][k], At[m][k], acc[ai][bj][m][n], 0, 0, 0); __builtin_amdgcn_s_setprio(0); } while (0)
; #define PG8_WAIT_V(n) asm volatile("s_waitcnt vmcnt(" #n ")" ::: "memory")
; #define PG8_BAR __builtin_amdgcn_s_barrier()
;     __device__ __forceinline__ void operator()(const f32x4 (&acc)[2][2][4][2], const Unit& u, int wr, int wc, int fr, int fq) const {
;         const int row0 = u.pm * BM + wr * 64 + fr, col0 = u.pn * BM + wc * 32 + 8 * fq;
;         if (u.part) {
;             float* base = tailacc + (size_t)(u.part - 1) * slab - (size_t)tail_row0 * tail_ld;
; #pragma unroll
;             for (int ai = 0; ai < 2; ++ai)
; #pragma unroll
;                 for (int m = 0; m < 4; ++m) { float* rowp = base + (size_t)(row0 + ai * HALF + m * 16) * tail_ld + col0;
; #pragma unroll
;                     for (int bj = 0; bj < 2; ++bj)
; #pragma unroll
;                         for (int n = 0; n < 2; ++n) *(f32x4*)(rowp + bj * HALF + 4 * n) = acc[ai][bj][m][n]; }
; template <class Epi>
; __device__ __forceinline__ void gemm_phase(LAS unsigned char* lds, const Gemm g, const StaticOrder& S, const Epi& E) {
;     ...
;             PG8_STAGE(PG8_SB(1, 1), b3 + hstepB, voffB);
;             PG8_WAIT_V(6); PG8_BAR; PG8_MMA(1, 1, At, B1); PG8_BAR;
	s_add_i32 s45, s45, s21
	v_lshl_add_u64 v[218:219], v[218:219], 0, s[12:13]
	s_mov_b32 m0, s45
	global_load_lds_dwordx4 v[218:219], off
	v_lshl_add_u64 v[218:219], v[220:221], 0, s[12:13]
	s_add_i32 m0, s45, 0x2000
	s_nop 0
	global_load_lds_dwordx4 v[218:219], off
	s_mov_b32 m0, s60
	v_lshl_add_u64 v[218:219], v[222:223], 0, s[12:13]
	ds_read_b128 v[170:173], v163 offset:49152
	ds_read_b128 v[174:177], v163 offset:50176
	ds_read_b128 v[178:181], v163 offset:51200
	ds_read_b128 v[182:185], v163 offset:52224
	ds_read_b128 v[186:189], v163 offset:53248
	ds_read_b128 v[190:193], v163 offset:54272
	ds_read_b128 v[194:197], v163 offset:55296
	ds_read_b128 v[198:201], v163 offset:56320
	global_load_lds_dwordx4 v[218:219], off
	v_lshl_add_u64 v[218:219], v[224:225], 0, s[12:13]
	s_mov_b32 m0, s61
	s_nop 0
	global_load_lds_dwordx4 v[218:219], off
	s_add_u32 s54, s54, 0x40080
	s_addc_u32 s55, s55, 0
	s_add_i32 s45, s56, s21
	v_lshl_add_u64 v[240:241], s[54:55], 0, v[138:139]
	s_mov_b32 m0, s45
	s_nop 0
	global_load_lds_dwordx4 v[240:241], off
	v_lshl_add_u64 v[240:241], s[54:55], 0, v[142:143]
	s_add_i32 m0, s45, 0x2000
	s_nop 0
	global_load_lds_dwordx4 v[240:241], off
	s_waitcnt vmcnt(8) lgkmcnt(0)
	s_barrier
	s_nop 0
	v_mfma_f32_16x16x32_bf16 v[60:63], v[150:153], v[170:173], v[60:63]
	v_mfma_f32_16x16x32_bf16 v[56:59], v[158:161], v[170:173], v[56:59]
	v_mfma_f32_16x16x32_bf16 v[52:55], v[150:153], v[178:181], v[52:55]
	v_mfma_f32_16x16x32_bf16 v[44:47], v[158:161], v[178:181], v[44:47]
	v_mfma_f32_16x16x32_bf16 v[36:39], v[150:153], v[186:189], v[36:39]
	v_mfma_f32_16x16x32_bf16 v[28:31], v[158:161], v[186:189], v[28:31]
	v_mfma_f32_16x16x32_bf16 v[20:23], v[150:153], v[194:197], v[20:23]
	v_mfma_f32_16x16x32_bf16 v[12:15], v[158:161], v[194:197], v[12:15]
	v_mfma_f32_16x16x32_bf16 v[60:63], v[154:157], v[174:177], v[60:63]
	v_mfma_f32_16x16x32_bf16 v[56:59], v[166:169], v[174:177], v[56:59]
	v_mfma_f32_16x16x32_bf16 v[52:55], v[154:157], v[182:185], v[52:55]
	v_mfma_f32_16x16x32_bf16 v[44:47], v[166:169], v[182:185], v[44:47]
	v_mfma_f32_16x16x32_bf16 v[36:39], v[154:157], v[190:193], v[36:39]
	v_mfma_f32_16x16x32_bf16 v[28:31], v[166:169], v[190:193], v[28:31]
	v_mfma_f32_16x16x32_bf16 v[20:23], v[154:157], v[198:201], v[20:23]
	v_mfma_f32_16x16x32_bf16 v[12:15], v[166:169], v[198:201], v[12:15]
	v_mfma_f32_16x16x32_bf16 v[48:51], v[202:205], v[170:173], v[48:51]
	v_mfma_f32_16x16x32_bf16 v[40:43], v[210:213], v[170:173], v[40:43]
	v_mfma_f32_16x16x32_bf16 v[32:35], v[202:205], v[178:181], v[32:35]
	v_mfma_f32_16x16x32_bf16 v[24:27], v[210:213], v[178:181], v[24:27]
	v_mfma_f32_16x16x32_bf16 v[16:19], v[202:205], v[186:189], v[16:19]
	v_mfma_f32_16x16x32_bf16 v[8:11], v[210:213], v[186:189], v[8:11]
	v_mfma_f32_16x16x32_bf16 v[4:7], v[202:205], v[194:197], v[4:7]
	v_mfma_f32_16x16x32_bf16 v[0:3], v[210:213], v[194:197], v[0:3]
	v_mfma_f32_16x16x32_bf16 v[48:51], v[206:209], v[174:177], v[48:51]
	v_mfma_f32_16x16x32_bf16 v[40:43], v[214:217], v[174:177], v[40:43]
	v_mfma_f32_16x16x32_bf16 v[32:35], v[206:209], v[182:185], v[32:35]
	v_mfma_f32_16x16x32_bf16 v[24:27], v[214:217], v[182:185], v[24:27]
	v_mfma_f32_16x16x32_bf16 v[16:19], v[206:209], v[190:193], v[16:19]
	v_mfma_f32_16x16x32_bf16 v[8:11], v[214:217], v[190:193], v[8:11]
	v_mfma_f32_16x16x32_bf16 v[4:7], v[206:209], v[198:201], v[4:7]
	v_mfma_f32_16x16x32_bf16 v[0:3], v[214:217], v[198:201], v[0:3]
	s_nop 0
	s_add_u32 s50, s50, 0x100
	s_addc_u32 s51, s51, 0
	s_add_u32 s41, s41, 0x100
	s_addc_u32 s43, s43, 0
	s_cmp_ge_i32 s77, s76
	s_mov_b32 s45, s77
	s_barrier
	s_cbranch_scc0 .LBB0_1146
	v_lshl_add_u32 v150, s8, 8, v133
	v_lshl_or_b32 v154, s44, 8, v162
	s_cmp_lg_u32 s75, 0
	v_ashrrev_i32_e32 v155, 31, v154
	v_or_b32_e32 v160, 16, v150
	v_or_b32_e32 v158, 32, v150
	v_or_b32_e32 v156, 48, v150
	s_cbranch_scc0 .LBB0_1149
	s_add_i32 s8, s75, -1
	s_lshl_b64 s[44:45], s[8:9], 21
	s_add_u32 s44, s92, s44
	s_addc_u32 s45, s93, s45
	v_lshl_add_u64 v[152:153], v[154:155], 2, s[44:45]
	v_ashrrev_i32_e32 v151, 31, v150
	v_ashrrev_i32_e32 v161, 31, v160
	v_lshl_add_u64 v[152:153], v[152:153], 0, s[22:23]
	v_lshlrev_b64 v[166:167], 12, v[150:151]
	v_lshlrev_b64 v[168:169], 12, v[160:161]
	v_lshl_add_u64 v[166:167], v[152:153], 0, v[166:167]
	v_lshl_add_u64 v[168:169], v[152:153], 0, v[168:169]
	v_ashrrev_i32_e32 v159, 31, v158
	global_store_dwordx4 v[166:167], v[124:127], off
	global_store_dwordx4 v[166:167], v[120:123], off offset:16
	global_store_dwordx4 v[166:167], v[112:115], off offset:512
	global_store_dwordx4 v[166:167], v[104:107], off offset:528
	global_store_dwordx4 v[168:169], v[116:119], off
	global_store_dwordx4 v[168:169], v[108:111], off offset:16
	global_store_dwordx4 v[168:169], v[96:99], off offset:512
	global_store_dwordx4 v[168:169], v[88:91], off offset:528
	v_lshlrev_b64 v[168:169], 12, v[158:159]
	v_lshl_add_u64 v[168:169], v[152:153], 0, v[168:169]
	v_ashrrev_i32_e32 v157, 31, v156
	global_store_dwordx4 v[168:169], v[100:103], off
	global_store_dwordx4 v[168:169], v[92:95], off offset:16
	global_store_dwordx4 v[168:169], v[80:83], off offset:512
	global_store_dwordx4 v[168:169], v[72:75], off offset:528
	v_lshlrev_b64 v[168:169], 12, v[156:157]
	v_lshl_add_u64 v[152:153], v[152:153], 0, v[168:169]
	v_add_co_u32_e32 v168, vcc, s68, v166
	global_store_dwordx4 v[152:153], v[84:87], off
	global_store_dwordx4 v[152:153], v[76:79], off offset:16
	global_store_dwordx4 v[152:153], v[68:71], off offset:512
	global_store_dwordx4 v[152:153], v[64:67], off offset:528
	v_addc_co_u32_e32 v169, vcc, 0, v167, vcc
	v_lshl_add_u64 v[152:153], v[166:167], 0, s[24:25]
	global_store_dwordx4 v[168:169], v[60:63], off
	global_store_dwordx4 v[152:153], v[56:59], off offset:16
	global_store_dwordx4 v[152:153], v[48:51], off offset:512
	global_store_dwordx4 v[152:153], v[40:43], off offset:528
	v_add_co_u32_e32 v168, vcc, s69, v166
	v_lshl_add_u64 v[152:153], v[166:167], 0, s[26:27]
	s_nop 0
	v_addc_co_u32_e32 v169, vcc, 0, v167, vcc
	global_store_dwordx4 v[168:169], v[52:55], off
	global_store_dwordx4 v[152:153], v[44:47], off offset:16
	global_store_dwordx4 v[152:153], v[32:35], off offset:512
	global_store_dwordx4 v[152:153], v[24:27], off offset:528
	v_add_co_u32_e32 v168, vcc, s70, v166
	v_lshl_add_u64 v[152:153], v[166:167], 0, s[28:29]
	s_nop 0
	v_addc_co_u32_e32 v169, vcc, 0, v167, vcc
	global_store_dwordx4 v[168:169], v[36:39], off
	global_store_dwordx4 v[152:153], v[28:31], off offset:16
	global_store_dwordx4 v[152:153], v[16:19], off offset:512
	global_store_dwordx4 v[152:153], v[8:11], off offset:528
	v_lshl_add_u64 v[152:153], v[166:167], 0, s[36:37]
	v_add_co_u32_e32 v166, vcc, 0xb0000, v166
	s_nop 1
	v_addc_co_u32_e32 v167, vcc, 0, v167, vcc
	global_store_dwordx4 v[166:167], v[20:23], off
	global_store_dwordx4 v[152:153], v[12:15], off offset:16
	global_store_dwordx4 v[152:153], v[4:7], off offset:512
	global_store_dwordx4 v[152:153], v[0:3], off offset:528
	s_cbranch_execnz .LBB0_1131
	s_branch .LBB0_1130
